# baseline (speedup 1.0000x reference)
; DEVI void run_phase(const int ph, const Params& P, char* shmc, const int wave_u) {
;     ...
;   if (ph != ONLY_PH) return;
;     ...
;   bf16* shm = (bf16*)shmc;
;   char* ws = P.ws; float* out = P.out;
;   asm volatile("" : "+s"(ws), "+s"(out));
;   bf16* w_in_t = (bf16*)(ws + WS_WIN); bf16* w_uq_t = (bf16*)(ws + WS_WUQ); bf16* w_ukv_t = (bf16*)(ws + WS_WUKV);
;   bf16* w_br_t = (bf16*)(ws + WS_WBR); bf16* w_out_t = (bf16*)(ws + WS_WOUT); bf16* pb = (bf16*)(ws + WS_PB);
;   float* rs0 = (float*)(ws + WS_RS0); float* ssq = (float*)(ws + WS_SSQ); float* rs1 = (float*)(ws + WS_RS1); float* rs2 = (float*)(ws + WS_RS2);
;   bf16* xb = (bf16*)(ws + WS_XB); bf16* qm = (bf16*)(ws + WS_XB);
;   bf16* sbq = (bf16*)(ws + WS_SBQ); bf16* sbk_p = (bf16*)(ws + WS_SBK_P); bf16* sbk_s = (bf16*)(ws + WS_SBK_S);
;   bf16* sbv_p = (bf16*)(ws + WS_SBV_P); bf16* sbv_s = (bf16*)(ws + WS_SBV_S); bf16* cq = (bf16*)(ws + WS_CQ);
;   bf16* ckva = (bf16*)(ws + WS_CKVA); bf16* kn_p = (bf16*)(ws + WS_KN_P); bf16* kn_s = (bf16*)(ws + WS_KN_S);
;   bf16* vm_p = (bf16*)(ws + WS_VM_P); bf16* vm_s = (bf16*)(ws + WS_VM_S); bf16* kr_p = (bf16*)(ws + WS_KR_P); bf16* kr_s = (bf16*)(ws + WS_KR_S);
;   bf16* ocat = (bf16*)(ws + WS_OCAT); bf16* merged = (bf16*)(ws + WS_MERGED); bf16* hid = (bf16*)(ws + WS_HID); bf16* ub = (bf16*)(ws + WS_U);
;   bf16* w_up_t = (bf16*)(ws + WS_WUP); bf16* w_dn_t = (bf16*)(ws + WS_WDN); bf16* w_pg_t = (bf16*)(ws + WS_WPG); bf16* w_ple_t = (bf16*)(ws + WS_WPLE);
;   bf16* T = (bf16*)(ws + WS_T); float* Tf = (float*)(ws + WS_TF);
;   bf16* gates = (bf16*)out;
;   const int G = gridDim.x;
;     ...
;   __syncthreads();
;   const uint4 t = sh;
;   XcdBarrier b; b.bar = bar;
;   b.x = __builtin_amdgcn_readfirstlane(t.x); b.nloc = __builtin_amdgcn_readfirstlane(t.y); b.nx = __builtin_amdgcn_readfirstlane(t.z);
.LBB0_20:
	s_or_b64 exec, exec, s[4:5]
	s_load_dwordx16 s[36:51], s[0:1], 0x0
	s_load_dwordx16 s[4:19], s[0:1], 0x40
	s_load_dwordx16 s[52:67], s[0:1], 0x80
	v_readlane_b32 s0, v251, 2
	s_and_b32 s31, s0, 0xffffffc0
	s_cmpk_lt_i32 s2, 0x200
	s_cselect_b64 s[0:1], -1, 0
	v_writelane_b32 v251, s0, 13
	s_cmpk_lt_i32 s2, 0x90
	s_mov_b32 s24, s2
	v_writelane_b32 v251, s1, 14
	s_cselect_b64 s[0:1], -1, 0
	s_lshl_b32 s20, s2, 3
	s_waitcnt lgkmcnt(0)
	s_lshl_b32 s34, s30, 3
	v_writelane_b32 v251, s0, 15
	s_cmpk_lt_i32 s2, 0x840
	v_mov_b32_e32 v33, 0
	v_writelane_b32 v251, s1, 16
	s_cselect_b64 s[0:1], -1, 0
	v_writelane_b32 v251, s0, 17
	s_cmp_lg_u64 s[64:65], 0
	s_nop 0
	v_writelane_b32 v251, s1, 18
	s_cselect_b64 s[0:1], -1, 0
	v_writelane_b32 v251, s0, 19
	s_cmpk_lt_i32 s2, 0x100
	s_barrier
	v_writelane_b32 v251, s1, 20
	s_cselect_b64 s[0:1], -1, 0
	v_writelane_b32 v251, s0, 21
	s_cmpk_lt_i32 s2, 0x80
	s_nop 0
	v_writelane_b32 v251, s1, 22
	s_cselect_b64 s[0:1], -1, 0
	v_writelane_b32 v251, s0, 23
	ds_read_b96 v[2:4], v33
	s_mov_b32 s26, s30
	v_writelane_b32 v251, s1, 24
	v_writelane_b32 v251, s52, 25
	s_cmp_lg_u64 s[56:57], 0
	s_cselect_b64 s[0:1], -1, 0
	v_writelane_b32 v251, s53, 26
	v_writelane_b32 v251, s54, 27
	v_writelane_b32 v251, s55, 28
	v_writelane_b32 v251, s56, 29
	v_writelane_b32 v251, s57, 30
	v_writelane_b32 v251, s58, 31
	v_writelane_b32 v251, s59, 32
	v_writelane_b32 v251, s60, 33
	v_writelane_b32 v251, s61, 34
	v_writelane_b32 v251, s62, 35
	v_writelane_b32 v251, s63, 36
	v_writelane_b32 v251, s64, 37
	v_writelane_b32 v251, s65, 38
	v_writelane_b32 v251, s66, 39
	v_writelane_b32 v251, s67, 40
	v_writelane_b32 v251, s0, 41
	s_cmpk_lt_i32 s2, 0x500
	s_mov_b32 s53, 0
	v_writelane_b32 v251, s1, 42
	s_cselect_b64 s[0:1], -1, 0
	v_writelane_b32 v251, s0, 43
	s_cmpk_lt_i32 s2, 0x59c
	s_mov_b32 s52, s24
	v_writelane_b32 v251, s1, 44
	s_cselect_b64 s[0:1], -1, 0
	v_writelane_b32 v251, s0, 45
	s_cmpk_lt_i32 s2, 0x882
	s_mul_i32 s64, s26, 0x3000
	v_writelane_b32 v251, s1, 46
	s_cselect_b64 s[0:1], -1, 0
	v_writelane_b32 v251, s0, 47
	s_cmpk_lt_i32 s2, 0x1080
	s_mul_hi_i32 s65, s26, 0x3000
	v_writelane_b32 v251, s1, 48
	s_mul_hi_i32 s0, s2, 0x3e0f83e1
	s_cselect_b64 s[2:3], -1, 0
	s_lshr_b32 s1, s0, 31
	s_ashr_i32 s0, s0, 5
	s_add_i32 s0, s0, s1
	s_mul_i32 s1, s0, 0x84
	s_sub_i32 s1, s24, s1
	v_writelane_b32 v251, s2, 49
	s_lshl_b32 s1, s1, 6
	s_lshl_b32 s0, s0, 6
	v_writelane_b32 v251, s3, 50
	s_cmpk_gt_u32 s1, 0x1fff
	v_writelane_b32 v251, s0, 51
	s_cselect_b64 s[2:3], -1, 0
	v_writelane_b32 v251, s2, 52
	s_cmpk_lt_u32 s1, 0x2040
	v_mov_b32_e32 v186, 0x358637bd
	v_writelane_b32 v251, s3, 53
	v_writelane_b32 v251, s1, 54
	s_cselect_b64 s[0:1], -1, 0
	v_writelane_b32 v251, s0, 55
	s_cmp_lg_u64 s[4:5], 0
	v_mov_b32_e32 v187, 1
	v_writelane_b32 v251, s1, 56
	s_cselect_b64 s[0:1], -1, 0
	v_writelane_b32 v251, s0, 57
	s_cmpk_lt_i32 s24, 0xc0
	s_cselect_b64 s[2:3], -1, 0
	v_writelane_b32 v251, s1, 58
	s_mul_hi_i32 s0, s24, 0x2aaaaaab
	s_lshr_b32 s1, s0, 31
	s_ashr_i32 s0, s0, 2
	s_add_i32 s0, s0, s1
	s_mul_i32 s1, s0, 24
	v_writelane_b32 v251, s2, 59
	s_sub_i32 s1, s24, s1
	s_lshl_b32 s1, s1, 6
	v_writelane_b32 v251, s3, 60
	v_writelane_b32 v251, s1, 61
	s_lshl_b32 s0, s0, 6
	v_writelane_b32 v251, s0, 62
	v_writelane_b32 v251, s4, 63
	s_cmp_lg_u64 s[8:9], 0
	s_cselect_b64 s[0:1], -1, 0
	v_writelane_b32 v252, s5, 0
	v_writelane_b32 v252, s6, 1
	v_writelane_b32 v252, s7, 2
	v_writelane_b32 v252, s8, 3
	v_writelane_b32 v252, s9, 4
	v_writelane_b32 v252, s10, 5
	v_writelane_b32 v252, s11, 6
	v_writelane_b32 v252, s12, 7
	v_writelane_b32 v252, s13, 8
	v_writelane_b32 v252, s14, 9
	v_writelane_b32 v252, s15, 10
	v_writelane_b32 v252, s16, 11
	v_writelane_b32 v252, s17, 12
	v_writelane_b32 v252, s18, 13
	v_writelane_b32 v252, s19, 14
	v_writelane_b32 v252, s0, 15
	s_ashr_i32 s25, s24, 31
	s_waitcnt lgkmcnt(0)
	v_readfirstlane_b32 s4, v2
	v_writelane_b32 v252, s1, 16
	s_lshr_b32 s0, s25, 28
	s_add_i32 s0, s24, s0
	s_and_b32 s1, s0, -16
	s_sub_i32 s1, s24, s1
	s_cmp_gt_i32 s1, -1
	s_cselect_b64 s[2:3], -1, 0
	v_writelane_b32 v252, s2, 17
	s_lshl_b32 s0, s0, 2
	s_andn2_b32 s0, s0, 63
	v_writelane_b32 v252, s3, 18
	v_writelane_b32 v252, s0, 19
	s_lshl_b32 s0, s1, 6
	s_cmpk_lt_i32 s24, 0x400
	v_writelane_b32 v252, s0, 20
	s_cselect_b64 s[0:1], -1, 0
	v_writelane_b32 v252, s0, 21
	s_mov_b32 s5, s53
	v_mov_b32_e32 v188, 0xff800000
	v_writelane_b32 v252, s1, 22
	s_lshr_b32 s0, s25, 27
	s_add_i32 s0, s24, s0
	s_and_b32 s1, s0, 0xffffffe0
	s_sub_i32 s1, s24, s1
	s_cmp_gt_i32 s1, -1
	s_cselect_b64 s[2:3], -1, 0
	v_writelane_b32 v252, s2, 23
	s_lshl_b32 s0, s0, 1
	s_andn2_b32 s0, s0, 63
	v_writelane_b32 v252, s3, 24
	v_writelane_b32 v252, s0, 25
	s_lshl_b32 s0, s1, 6
	v_writelane_b32 v252, s0, 26
	s_lshl_b64 s[2:3], s[24:25], 12
	s_lshl_b32 s6, s4, 6
	v_writelane_b32 v252, s2, 27
	s_ashr_i32 s27, s30, 31
	s_mov_b32 s0, s30
	s_mov_b32 s1, s53
	s_add_i32 s4, s6, 0x500
	v_writelane_b32 v252, s3, 28
	s_lshl_b64 s[2:3], s[52:53], 12
	s_lshl_b64 s[4:5], s[4:5], 2
	s_lshl_b64 s[82:83], s[26:27], 12
	v_writelane_b32 v252, s2, 29
	s_lshl_b64 s[68:69], s[0:1], 12
	v_mov_b32_e32 v189, 0x220000
	v_writelane_b32 v252, s3, 30
	s_add_u32 s2, s28, s4
	s_addc_u32 s3, s29, s5
	s_add_i32 s4, s6, 0x900
	s_mov_b32 s5, s53
	v_writelane_b32 v252, s2, 31
	s_lshl_b64 s[4:5], s[4:5], 2
	v_not_b32_e32 v190, 63
	v_writelane_b32 v252, s3, 32
	s_add_u32 s2, s28, s4
	s_addc_u32 s3, s29, s5
	v_readlane_b32 s4, v251, 3
	v_writelane_b32 v252, s2, 33
	v_readlane_b32 s10, v251, 9
	v_readlane_b32 s11, v251, 10
	v_writelane_b32 v252, s3, 34
	s_add_u32 s2, s10, 0x227e8200
	s_addc_u32 s3, s11, 0
; DEVI void run_phase(const int ph, const Params& P, char* shmc, const int wave_u) {
;     ...
;       const int nj = 16 * 8; const int ext = nj % G;
;       const int nvb = ext ? G - ext : G; const int vb = ext ? (int)blockIdx.x - ext : (int)blockIdx.x;
;       if (vb >= 0) transpose_job<0>(P.w_up, DFF, P.g_ffn_pre, w_up_t, 2048, DFF, (unsigned short*)shmc, wave_u, vb, nvb);
;     ...
;       const int ntl = (DFF / 256) * (MT / 256); const int ext = ntl % G;
;       const int nvb = ext ? G - ext : G; const int vb = ext ? (int)blockIdx.x - ext : (int)blockIdx.x;
	v_writelane_b32 v252, s2, 35
	v_readlane_b32 s5, v251, 4
	v_readlane_b32 s6, v251, 5
	v_writelane_b32 v252, s3, 36
	s_add_u32 s2, s10, 0x227eb400
	s_addc_u32 s3, s11, 0
	v_writelane_b32 v252, s2, 37
	v_readlane_b32 s7, v251, 6
	v_readfirstlane_b32 s29, v3
	v_writelane_b32 v252, s3, 38
	s_add_u32 s2, s10, 0x227eb500
	s_addc_u32 s3, s11, 0
	v_writelane_b32 v252, s2, 39
	s_lshl_b32 s28, s30, 9
	v_readlane_b32 s8, v251, 7
	v_writelane_b32 v252, s3, 40
	s_lshl_b32 s2, s24, 9
	s_cmp_eq_u64 s[10:11], 0
	v_writelane_b32 v252, s2, 41
	s_cselect_b64 s[2:3], -1, 0
	v_writelane_b32 v252, s2, 42
	v_readlane_b32 s9, v251, 8
	v_mov_b32_e32 v191, 0x42800000
	v_writelane_b32 v252, s3, 43
	s_abs_i32 s2, s30
	v_cvt_f32_u32_e32 v2, s2
	s_sub_i32 s3, 0, s2
	v_mov_b64_e32 v[146:147], 0xbfc8000
	s_movk_i32 s95, 0x100
	v_rcp_iflag_f32_e32 v2, v2
	s_mov_b64 s[88:89], 0x1a7c8180
	s_mov_b64 s[78:79], 0x81c8180
	s_mov_b64 s[76:77], 0x2480100
	v_mul_f32_e32 v2, 0x4f7ffffe, v2
	v_cvt_u32_f32_e32 v2, v2
	s_mov_b64 s[86:87], 0x2500100
	s_mov_b64 s[90:91], 0x1dde8900
	s_mov_b64 s[80:81], 0x2480900
	v_readfirstlane_b32 s4, v2
	s_mul_i32 s3, s3, s4
	s_mul_hi_u32 s3, s4, s3
	s_add_i32 s4, s4, s3
	s_mul_hi_u32 s3, s4, 0x840
	s_mul_i32 s3, s3, s2
	s_sub_i32 s3, 0x840, s3
	s_sub_i32 s5, s3, s2
	s_cmp_ge_u32 s3, s2
	s_cselect_b32 s3, s5, s3
	s_sub_i32 s5, s3, s2
	s_cmp_ge_u32 s3, s2
	s_cselect_b32 s3, s5, s3
	s_sub_i32 s5, s30, s3
	v_writelane_b32 v252, s5, 44
	s_sub_i32 s5, s24, s3
	s_cmp_gt_i32 s5, -1
	s_cselect_b64 s[6:7], -1, 0
	v_writelane_b32 v252, s6, 45
	s_cmpk_lt_u32 s5, 0x1000
	v_lshrrev_b32_e32 v2, 20, v0
	v_writelane_b32 v252, s7, 46
	s_cselect_b64 s[6:7], -1, 0
	v_writelane_b32 v252, s6, 47
	s_lshl_b32 s3, s5, 1
	v_lshrrev_b32_e32 v0, 10, v0
	v_writelane_b32 v252, s7, 48
	s_and_b32 s6, s3, 0x1fc0
	v_writelane_b32 v252, s6, 49
	s_lshl_b32 s6, s5, 6
	v_writelane_b32 v252, s6, 50
	s_and_b32 s6, s6, 0x7c0
	s_cmpk_lt_i32 s5, 0x400
	v_writelane_b32 v252, s6, 51
	s_cselect_b64 s[6:7], -1, 0
	v_writelane_b32 v252, s6, 52
	s_and_b32 s3, s3, 0x7fffffc0
	s_cmpk_lt_i32 s5, 0x80
	v_writelane_b32 v252, s7, 53
	v_writelane_b32 v252, s3, 54
	s_cselect_b64 s[6:7], -1, 0
	s_lshr_b32 s3, s4, 25
	s_mul_i32 s3, s3, s2
	s_sub_i32 s3, 0x80, s3
	v_writelane_b32 v252, s5, 55
	s_sub_i32 s5, s3, s2
	s_cmp_ge_u32 s3, s2
	s_cselect_b32 s3, s5, s3
	s_sub_i32 s5, s3, s2
	s_cmp_ge_u32 s3, s2
	v_writelane_b32 v252, s6, 56
	s_cselect_b32 s3, s5, s3
	s_mov_b32 s3, 0
	s_sub_i32 s5, s30, s3
	v_writelane_b32 v252, s7, 57
	v_writelane_b32 v252, s5, 58
	s_sub_i32 s5, s24, s3
	s_cmp_gt_i32 s5, -1
	s_cselect_b64 s[6:7], -1, 0
	v_writelane_b32 v252, s6, 59
	s_cmpk_lt_u32 s5, 0x1000
	v_writelane_b32 v253, s5, 0
	v_writelane_b32 v252, s7, 60
	s_cselect_b64 s[6:7], -1, 0
	v_writelane_b32 v252, s6, 61
	s_lshr_b32 s3, s5, 1
	s_and_b32 s3, s3, 0x7c0
	v_writelane_b32 v252, s7, 62
	v_writelane_b32 v252, s3, 63
	s_mul_hi_u32 s3, s4, 0x882
	s_mul_i32 s3, s3, s2
	s_lshl_b32 s4, s5, 6
	s_sub_i32 s3, 0x882, s3
	v_writelane_b32 v253, s4, 1
	s_and_b32 s4, s4, 0x1fc0
	v_writelane_b32 v253, s4, 2
	s_sub_i32 s4, s3, s2
	s_cmp_ge_u32 s3, s2
	s_cselect_b32 s3, s4, s3
	s_sub_i32 s4, s3, s2
	s_cmp_ge_u32 s3, s2
	s_cselect_b32 s4, s4, s3
	s_sub_i32 s6, s24, s4
	s_cmp_gt_i32 s6, -1
	s_cselect_b64 s[2:3], -1, 0
	v_writelane_b32 v253, s2, 3
	s_ashr_i32 s35, s34, 31
	s_mov_b32 s7, s53
	v_writelane_b32 v253, s3, 4
	s_sub_i32 s2, s30, s4
	s_ashr_i32 s3, s2, 31
	s_lshl_b64 s[2:3], s[2:3], 12
	v_writelane_b32 v253, s2, 5
	v_readfirstlane_b32 s30, v4
	s_sub_i32 s18, 0, s29
	v_writelane_b32 v253, s3, 6
	s_lshl_b32 s2, s24, 8
	v_writelane_b32 v253, s2, 7
	s_lshl_b32 s2, s26, 8
	v_writelane_b32 v253, s2, 8
	s_lshl_b32 s2, s24, 5
	v_writelane_b32 v253, s2, 9
	s_lshl_b32 s2, s26, 5
	v_writelane_b32 v253, s2, 10
	v_writelane_b32 v253, s20, 11
	s_add_i32 s2, s20, 0xffffc000
	v_writelane_b32 v253, s2, 12
	s_lshl_b32 s2, s24, 2
	v_writelane_b32 v253, s2, 13
	s_lshl_b32 s2, s26, 2
	v_writelane_b32 v253, s2, 14
	s_add_i32 s2, s24, 4
	v_writelane_b32 v253, s2, 15
	s_add_i32 s2, s24, 0xfffffe74
	v_writelane_b32 v253, s2, 16
	s_lshl_b32 s2, s24, 1
	v_writelane_b32 v253, s2, 17
	s_lshl_b32 s2, s26, 1
	v_writelane_b32 v253, s2, 18
	s_lshl_b64 s[2:3], s[34:35], 11
	s_sub_i32 s19, 0, s30
	s_lshl_b64 s[54:55], s[6:7], 12
	v_writelane_b32 v253, s2, 19
	s_lshl_b64 s[56:57], s[26:27], 13
	s_lshl_b64 s[58:59], s[6:7], 13
	v_writelane_b32 v253, s3, 20
	s_add_u32 s2, s56, s58
	s_addc_u32 s3, s57, s59
	s_ashr_i32 s5, s4, 31
	s_lshl_b64 s[12:13], s[4:5], 13
	s_sub_u32 s20, s2, s12
	s_subb_u32 s21, s3, s13
	s_add_u32 s2, s20, 0xc0c8000
	s_addc_u32 s3, s21, 0
	v_writelane_b32 v253, s2, 21
	s_lshl_b64 s[8:9], s[4:5], 15
	v_or_b32_e32 v0, v0, v2
	v_writelane_b32 v253, s3, 22
	s_lshl_b64 s[2:3], s[26:27], 15
	s_sub_u32 s10, s2, s8
	v_writelane_b32 v253, s10, 23
	s_subb_u32 s10, s3, s9
	v_writelane_b32 v253, s10, 24
	s_lshl_b64 s[10:11], s[6:7], 14
	s_lshl_b64 s[6:7], s[26:27], 14
	s_add_u32 s16, s6, s10
	s_addc_u32 s17, s7, s11
	s_lshl_b64 s[14:15], s[4:5], 14
	s_sub_u32 s60, s16, s14
	s_subb_u32 s61, s17, s15
	s_lshl_b64 s[22:23], s[26:27], 16
	s_lshl_b64 s[16:17], s[4:5], 16
	s_sub_u32 s16, s22, s16
	v_writelane_b32 v253, s22, 25
	s_subb_u32 s17, s23, s17
	s_or_b32 s62, s10, 16
	v_writelane_b32 v253, s23, 26
	v_writelane_b32 v253, s16, 27
	s_mul_i32 s22, s4, 0x3000
	s_mov_b32 s63, s11
	v_writelane_b32 v253, s17, 28
	s_sub_u32 s16, s56, s12
	s_subb_u32 s17, s57, s13
	v_writelane_b32 v253, s16, 29
	s_add_u32 s5, s6, s58
	v_cvt_f32_u32_e32 v3, s30
	v_writelane_b32 v253, s17, 30
	s_addc_u32 s16, s7, s59
	s_sub_u32 s5, s5, s14
	s_subb_u32 s14, s16, s15
; DEVI void run_phase(const int ph, const Params& P, char* shmc, const int wave_u) {
;     ...
;   if (ph != ONLY_PH) return;
;     ...
;   bf16* shm = (bf16*)shmc;
;   char* ws = P.ws; float* out = P.out;
;   asm volatile("" : "+s"(ws), "+s"(out));
;   bf16* w_in_t = (bf16*)(ws + WS_WIN); bf16* w_uq_t = (bf16*)(ws + WS_WUQ); bf16* w_ukv_t = (bf16*)(ws + WS_WUKV);
;   bf16* w_br_t = (bf16*)(ws + WS_WBR); bf16* w_out_t = (bf16*)(ws + WS_WOUT); bf16* pb = (bf16*)(ws + WS_PB);
;   float* rs0 = (float*)(ws + WS_RS0); float* ssq = (float*)(ws + WS_SSQ); float* rs1 = (float*)(ws + WS_RS1); float* rs2 = (float*)(ws + WS_RS2);
;   bf16* xb = (bf16*)(ws + WS_XB); bf16* qm = (bf16*)(ws + WS_XB);
;   bf16* sbq = (bf16*)(ws + WS_SBQ); bf16* sbk_p = (bf16*)(ws + WS_SBK_P); bf16* sbk_s = (bf16*)(ws + WS_SBK_S);
;   bf16* sbv_p = (bf16*)(ws + WS_SBV_P); bf16* sbv_s = (bf16*)(ws + WS_SBV_S); bf16* cq = (bf16*)(ws + WS_CQ);
;   bf16* ckva = (bf16*)(ws + WS_CKVA); bf16* kn_p = (bf16*)(ws + WS_KN_P); bf16* kn_s = (bf16*)(ws + WS_KN_S);
;   bf16* vm_p = (bf16*)(ws + WS_VM_P); bf16* vm_s = (bf16*)(ws + WS_VM_S); bf16* kr_p = (bf16*)(ws + WS_KR_P); bf16* kr_s = (bf16*)(ws + WS_KR_S);
;   bf16* ocat = (bf16*)(ws + WS_OCAT); bf16* merged = (bf16*)(ws + WS_MERGED); bf16* hid = (bf16*)(ws + WS_HID); bf16* ub = (bf16*)(ws + WS_U);
;   bf16* w_up_t = (bf16*)(ws + WS_WUP); bf16* w_dn_t = (bf16*)(ws + WS_WDN); bf16* w_pg_t = (bf16*)(ws + WS_WPG); bf16* w_ple_t = (bf16*)(ws + WS_WPLE);
;   bf16* T = (bf16*)(ws + WS_T); float* Tf = (float*)(ws + WS_TF);
;   bf16* gates = (bf16*)out;
;   const int G = gridDim.x;
	s_add_u32 s16, s5, 0xc0c8000
	s_addc_u32 s17, s14, 0
	v_writelane_b32 v253, s16, 31
	s_add_u32 s15, s64, s54
	v_rcp_iflag_f32_e32 v3, v3
	v_writelane_b32 v253, s17, 32
	s_addc_u32 s16, s65, s55
	s_mul_hi_i32 s17, s4, 0x3000
	s_sub_u32 s66, s15, s22
	s_subb_u32 s67, s16, s17
	v_writelane_b32 v253, s66, 33
	s_add_u32 s15, s56, s54
	v_mul_f32_e32 v3, 0x4f7ffffe, v3
	v_writelane_b32 v253, s67, 34
	v_writelane_b32 v253, s54, 35
	v_cvt_u32_f32_e32 v3, v3
	s_mov_b64 s[96:97], 0x1de68900
	v_writelane_b32 v253, s55, 36
	v_writelane_b32 v253, s56, 37
	s_addc_u32 s16, s57, s55
	s_sub_u32 s12, s15, s12
	v_writelane_b32 v253, s57, 38
	s_subb_u32 s13, s16, s13
	v_writelane_b32 v253, s12, 39
	s_mul_i32 s15, s4, 0x6000
	v_mul_lo_u32 v4, s19, v3
	v_writelane_b32 v253, s13, 40
	s_sub_u32 s12, s64, s22
	v_writelane_b32 v253, s64, 41
	s_subb_u32 s13, s65, s17
	s_mov_b64 s[54:55], 0x100
	v_writelane_b32 v253, s65, 42
	v_writelane_b32 v253, s12, 43
	s_mov_b64 s[56:57], 0x180
	s_mov_b64 s[64:65], 0x3dc8100
	v_writelane_b32 v253, s13, 44
	s_mul_i32 s12, s26, 0x6000
	s_add_u32 s12, s12, s58
	s_mul_hi_i32 s13, s26, 0x6000
	v_writelane_b32 v253, s58, 45
	s_addc_u32 s13, s13, s59
	s_sub_u32 s12, s12, s15
	s_mul_hi_i32 s15, s4, 0x6000
	s_subb_u32 s13, s13, s15
	s_add_u32 s16, s12, 0xc0c8000
	v_writelane_b32 v253, s59, 46
	s_addc_u32 s17, s13, 0
	v_writelane_b32 v253, s16, 47
	s_mul_hi_i32 s15, s4, 0xc000
	s_mul_i32 s4, s4, 0xc000
	v_writelane_b32 v253, s17, 48
	s_add_u32 s16, s20, 0x102c8000
	s_addc_u32 s17, s21, 0
	v_writelane_b32 v253, s16, 49
	s_mov_b64 s[58:59], 0x3e48100
	s_nop 0
	v_writelane_b32 v253, s17, 50
	s_add_u32 s16, s5, 0x102c8000
	s_addc_u32 s17, s14, 0
	v_writelane_b32 v253, s16, 51
	s_nop 1
	v_writelane_b32 v253, s17, 52
	s_add_u32 s16, s12, 0x102c8000
	s_addc_u32 s17, s13, 0
	v_writelane_b32 v253, s16, 53
	s_nop 1
	v_writelane_b32 v253, s17, 54
	s_add_u32 s16, s44, s60
	v_writelane_b32 v253, s60, 55
	s_addc_u32 s17, s45, s61
	s_nop 0
	v_writelane_b32 v253, s61, 56
	v_writelane_b32 v253, s16, 57
	s_mov_b64 s[60:61], 0x2480980
	s_nop 0
	v_writelane_b32 v253, s17, 58
	s_mul_i32 s17, s26, 0xc000
	s_mul_hi_i32 s16, s26, 0xc000
	s_add_u32 s22, s17, s10
	s_addc_u32 s23, s16, s11
	s_sub_u32 s4, s22, s4
	s_subb_u32 s15, s23, s15
	s_add_u32 s22, s44, s4
	s_addc_u32 s23, s45, s15
	v_writelane_b32 v253, s22, 59
	s_nop 1
	v_writelane_b32 v253, s23, 60
	s_add_u32 s22, s44, s10
	s_addc_u32 s23, s45, s11
	s_add_u32 s4, s2, s10
	v_writelane_b32 v253, s62, 61
	s_addc_u32 s10, s3, s11
	s_sub_u32 s4, s4, s8
	v_writelane_b32 v253, s63, 62
	v_writelane_b32 v253, s22, 63
	s_subb_u32 s8, s10, s9
	s_or_b32 s4, s4, 16
	v_writelane_b32 v254, s23, 0
	s_add_u32 s10, s44, s4
	v_writelane_b32 v254, s36, 1
	s_addc_u32 s11, s45, s8
	s_add_u32 s8, s20, 0x1dbc8000
	v_writelane_b32 v254, s37, 2
	v_writelane_b32 v254, s38, 3
	v_writelane_b32 v254, s39, 4
	v_writelane_b32 v254, s40, 5
	v_writelane_b32 v254, s41, 6
	v_writelane_b32 v254, s42, 7
	v_writelane_b32 v254, s43, 8
	v_writelane_b32 v254, s44, 9
	v_writelane_b32 v254, s45, 10
	v_writelane_b32 v254, s46, 11
	v_writelane_b32 v254, s47, 12
	v_writelane_b32 v254, s48, 13
	v_writelane_b32 v254, s49, 14
	v_writelane_b32 v254, s50, 15
	v_writelane_b32 v254, s51, 16
	v_writelane_b32 v254, s10, 17
	s_addc_u32 s9, s21, 0
	s_mov_b64 s[36:37], 0x3e48180
	v_writelane_b32 v254, s11, 18
	v_writelane_b32 v254, s8, 19
	s_mov_b64 s[42:43], 0x1a9c8080
	s_mov_b64 s[44:45], 0x7fc8100
	v_writelane_b32 v254, s9, 20
	s_add_u32 s8, s5, 0x1dbc8000
	s_addc_u32 s9, s14, 0
	v_writelane_b32 v254, s8, 21
	s_mov_b32 s5, s31
	s_mov_b64 s[14:15], 0x3dc8180
	v_writelane_b32 v254, s9, 22
	s_add_u32 s8, s12, 0x1dbc8000
	s_addc_u32 s9, s13, 0
	v_writelane_b32 v254, s8, 23
	s_add_i32 s4, s26, s24
	s_lshl_b32 s4, s4, 6
	v_writelane_b32 v254, s9, 24
	v_writelane_b32 v254, s4, 25
	s_mov_b32 s4, s26
	v_writelane_b32 v254, s4, 26
	s_lshl_b32 s8, s24, 6
	s_mov_b64 s[46:47], 0x1a7c8100
	v_writelane_b32 v254, s5, 27
	s_lshl_b32 s4, s26, 6
	v_writelane_b32 v254, s8, 28
	v_writelane_b32 v254, s4, 29
	s_add_i32 s4, s4, s8
	v_writelane_b32 v254, s4, 30
	v_writelane_b32 v254, s34, 31
	s_lshl_b64 s[8:9], s[34:35], 13
	s_mov_b32 s4, s24
	v_writelane_b32 v254, s35, 32
	v_writelane_b32 v254, s8, 33
	s_mov_b64 s[48:49], 0x81c8100
	s_mov_b64 s[50:51], 0x1a9c8100
	v_writelane_b32 v254, s9, 34
	s_lshl_b64 s[8:9], s[24:25], 14
	v_writelane_b32 v254, s4, 35
	s_add_u32 s6, s8, s6
	s_addc_u32 s7, s9, s7
	v_writelane_b32 v254, s5, 36
	v_writelane_b32 v254, s6, 37
	s_movk_i32 s4, 0x3ff
	v_and_or_b32 v0, v0, s4, v1
	v_writelane_b32 v254, s7, 38
	v_writelane_b32 v254, s29, 39
	s_add_u32 s6, s17, s8
	v_writelane_b32 v254, s30, 40
	s_addc_u32 s7, s16, s9
	v_writelane_b32 v254, s6, 41
	s_add_u32 s2, s2, s8
	v_cvt_f32_u32_e32 v1, s29
	v_writelane_b32 v254, s7, 42
	v_writelane_b32 v254, s8, 43
	s_addc_u32 s3, s3, s9
	s_or_b32 s2, s2, 16
	v_writelane_b32 v254, s9, 44
	v_writelane_b32 v254, s2, 45
	v_rcp_iflag_f32_e32 v1, v1
	s_mov_b64 s[40:41], 0x7fc8180
	v_writelane_b32 v254, s3, 46
	s_mov_b32 s3, s53
	v_writelane_b32 v254, s2, 47
	v_mul_f32_e32 v1, 0x4f7ffffe, v1
	v_cvt_u32_f32_e32 v1, v1
	v_writelane_b32 v254, s3, 48
	s_lshl_b64 s[2:3], s[52:53], 13
	s_add_u32 s4, s2, 0xc2d8000
	v_writelane_b32 v254, s4, 49
	s_addc_u32 s4, s3, 0
	v_writelane_b32 v254, s4, 50
	s_lshl_b64 s[0:1], s[0:1], 13
	v_writelane_b32 v254, s0, 51
	v_mul_lo_u32 v2, s18, v1
	v_mul_hi_u32 v2, v1, v2
	v_writelane_b32 v254, s1, 52
	s_add_u32 s0, s2, 0x104d8000
	v_writelane_b32 v254, s0, 53
	s_addc_u32 s0, s3, 0
	v_writelane_b32 v254, s0, 54
	s_add_u32 s0, s2, 0x177d8000
	v_writelane_b32 v254, s0, 55
	s_addc_u32 s0, s3, 0
	v_writelane_b32 v254, s0, 56
	s_add_u32 s0, s2, 0x1b9d8000
	v_writelane_b32 v254, s0, 57
	s_addc_u32 s0, s3, 0
	v_writelane_b32 v254, s0, 58
	s_add_u32 s0, s2, 0x1dbe9000
	v_writelane_b32 v254, s0, 59
	s_addc_u32 s0, s3, 0
	v_writelane_b32 v254, s0, 60
	s_add_i32 s0, 16, 0x18000
	v_writelane_b32 v254, s0, 61
	s_add_i32 s0, 16, 0x1c000
	v_writelane_b32 v254, s0, 62
	s_mov_b32 s0, 0
	v_writelane_b32 v254, s0, 63
	v_cmp_eq_u32_e64 s[0:1], 0, v0
	s_ashr_i32 s29, s28, 31
	v_add_u32_e32 v184, v1, v2
	v_writelane_b32 v255, s0, 0
	v_mul_hi_u32 v1, v3, v4
	v_add_u32_e32 v185, v3, v1
	v_writelane_b32 v255, s1, 1
	s_lshl_b64 s[0:1], s[28:29], 3
	v_writelane_b32 v255, s0, 2
	s_add_i32 s33, 16, 0x10000
	s_add_i32 s74, 16, 0x14000
	v_writelane_b32 v255, s1, 3
	s_lshl_b64 s[0:1], s[28:29], 4
	v_writelane_b32 v255, s0, 4
	s_mov_b64 s[10:11], 0x1de68180
	s_mov_b64 s[2:3], 0x2500880
	v_writelane_b32 v255, s1, 5
	v_writelane_b32 v255, s5, 6
	v_writelane_b32 v255, s82, 7
	s_mov_b64 s[34:35], 0x2500900
	s_mov_b64 s[52:53], 0x1dde8980
	v_writelane_b32 v255, s83, 8
	v_writelane_b32 v255, s68, 9
	s_mov_b64 s[62:63], 0x1de68980
	s_nop 0
	v_writelane_b32 v255, s69, 10
	v_writelane_b32 v255, s28, 11
	s_nop 1
	v_writelane_b32 v255, s29, 12
	s_branch .LBB0_24

; #define TJ_LOAD(tile_) do { const int n0_ = ((tile_) % ntn) * 64, k0_ = ((tile_) / ntn) * 64; const int sc_ = srccol<CM>(n0_ + cb); \
;     a = f32x4{0, 0, 0, 0}; b = f32x4{0, 0, 0, 0}; \
;     if (sc_ >= 0) { const float* s_ = src + (long)(k0_ + kk) * srcld + sc_; a = *(const f32x4*)s_; b = *(const f32x4*)(s_ + 4); } \
;     gg = g ? g[k0_ + kk] : 1.f; } while (0)
; template <int CM>
; DEVI void transpose_job(const float* __restrict__ src, int srcld, const float* __restrict__ g, bf16* __restrict__ dst,
;                         int K, int Ndst, unsigned short* lds, const int wave_u, const int vb, const int nvb) {
;     ...
;   int tile = vb;
;   if (tile < ntiles) TJ_LOAD(tile);
; DEVI void run_phase(const int ph, const Params& P, char* shmc, const int wave_u) {
;     ...
;       if (vb >= 0) {
;         unsigned short* tl = (unsigned short*)shmc;
;         transpose_job<0>(P.w_down, 2048, nullptr, w_dn_t, DFF, 2048, tl, wave_u, vb, nvb);
.LBB0_93:
	v_readlane_b32 s4, v252, 45
	v_readlane_b32 s5, v252, 46
	s_and_b64 vcc, exec, s[4:5]
	s_mov_b32 s5, s16
	s_cbranch_vccz .LBB0_146
	v_readlane_b32 s6, v252, 47
	v_readlane_b32 s7, v252, 48
	s_andn2_b64 vcc, exec, s[6:7]
	s_waitcnt vmcnt(0)
	v_mbcnt_lo_u32_b32 v0, -1, 0
	v_mbcnt_hi_u32_b32 v0, -1, v0
	s_cbranch_vccnz .LBB0_126
	s_waitcnt lgkmcnt(0)
	v_or_b32_e32 v1, s5, v0
	v_lshlrev_b32_e32 v0, 3, v0
	v_and_b32_e32 v12, 56, v0
	v_readlane_b32 s4, v252, 51
	v_ashrrev_i32_e32 v8, 3, v1
	v_readlane_b32 s16, v251, 25
	v_or_b32_e32 v2, s4, v12
	v_readlane_b32 s4, v252, 49
	v_readlane_b32 s24, v251, 33
	v_readlane_b32 s25, v251, 34
	v_add_u32_e32 v0, s4, v8
	v_ashrrev_i32_e32 v1, 31, v0
	v_lshlrev_b64 v[0:1], 13, v[0:1]
	v_lshl_add_u64 v[0:1], s[24:25], 0, v[0:1]
	v_lshlrev_b32_e32 v32, 2, v2
	v_lshl_add_u64 v[0:1], v[0:1], 0, v[32:33]
	global_load_dwordx4 v[4:7], v[0:1], off offset:16
	s_nop 0
	global_load_dwordx4 v[0:3], v[0:1], off
	s_movk_i32 s4, 0x90
	v_mul_lo_u32 v11, v8, s4
	v_readlane_b32 s4, v252, 44
	v_lshl_add_u32 v10, v12, 1, 16
	v_lshl_add_u32 v13, v8, 1, 16
	v_mul_u32_u24_e32 v14, 0x90, v12
	v_readlane_b32 s39, v252, 55
	s_lshl_b32 s9, s4, 6
	s_lshl_b32 s8, s39, 6
	v_or_b32_e32 v9, s9, v12
	v_add_u32_e32 v10, v10, v11
	v_add_u32_e32 v11, v13, v14
	v_lshlrev_b32_e32 v32, 1, v12
	v_readlane_b32 s17, v251, 26
	v_readlane_b32 s18, v251, 27
	v_readlane_b32 s19, v251, 28
	v_readlane_b32 s20, v251, 29
	v_readlane_b32 s21, v251, 30
	v_readlane_b32 s22, v251, 31
	v_readlane_b32 s23, v251, 32
	v_readlane_b32 s26, v251, 35
	v_readlane_b32 s27, v251, 36
	v_readlane_b32 s28, v251, 37
	v_readlane_b32 s29, v251, 38
	v_readlane_b32 s30, v251, 39
	v_readlane_b32 s31, v251, 40
	s_waitcnt vmcnt(0)
	s_branch .LBB0_123

; #define TJ_LOAD(tile_) do { const int n0_ = ((tile_) % ntn) * 64, k0_ = ((tile_) / ntn) * 64; const int sc_ = srccol<CM>(n0_ + cb); \
;     a = f32x4{0, 0, 0, 0}; b = f32x4{0, 0, 0, 0}; \
;     if (sc_ >= 0) { const float* s_ = src + (long)(k0_ + kk) * srcld + sc_; a = *(const f32x4*)s_; b = *(const f32x4*)(s_ + 4); } \
;     gg = g ? g[k0_ + kk] : 1.f; } while (0)
; template <int CM>
; DEVI void transpose_job(const float* __restrict__ src, int srcld, const float* __restrict__ g, bf16* __restrict__ dst,
;                         int K, int Ndst, unsigned short* lds, const int wave_u, const int vb, const int nvb) {
;     ...
;   for (; tile < ntiles; tile += nvb) {
;     const int n0 = (tile % ntn) * 64, k0 = (tile / ntn) * 64;
;     { u32x4 w = {cvtpk(a[0] * gg, a[1] * gg), cvtpk(a[2] * gg, a[3] * gg), cvtpk(b[0] * gg, b[1] * gg), cvtpk(b[2] * gg, b[3] * gg)};
;       *reinterpret_cast<u32x4*>(lds + kk * 72 + cb) = w; }
;     if (tile + nvb < ntiles) TJ_LOAD(tile + nvb);
;     __syncthreads();
;     { const int nn = tid >> 3, kb = (tid & 7) * 8; unsigned short e[8];
; #pragma unroll
;       for (int i = 0; i < 8; ++i) e[i] = lds[(kb + i) * 72 + nn];
;       u32x4 w = {(unsigned)e[0] | ((unsigned)e[1] << 16), (unsigned)e[2] | ((unsigned)e[3] << 16),
;                  (unsigned)e[4] | ((unsigned)e[5] << 16), (unsigned)e[6] | ((unsigned)e[7] << 16)};
;       *reinterpret_cast<u32x4*>(dst + (long)(n0 + nn) * K + k0 + kb) = w; }
;     __syncthreads();
.LBB0_123:
	v_readlane_b32 s4, v252, 44
	s_add_i32 s38, s39, s4
	s_cmpk_gt_i32 s38, 0xfff
	s_cselect_b64 s[6:7], -1, 0
	s_and_b64 vcc, exec, s[6:7]
	s_waitcnt vmcnt(1)
	v_cvt_pk_bf16_f32 v12, v0, v1
	v_cvt_pk_bf16_f32 v13, v2, v3
	v_cvt_pk_bf16_f32 v14, v4, v5
	v_cvt_pk_bf16_f32 v15, v6, v7
	ds_write_b128 v10, v[12:15]
	s_cbranch_vccnz .LBB0_122
	s_ashr_i32 s4, s38, 31
	s_lshr_b32 s4, s4, 27
	s_add_i32 s68, s38, s4
	s_and_b32 s4, s68, 0xffffffe0
	s_sub_i32 s4, s38, s4
	s_cmp_lt_i32 s4, 0
	s_cbranch_scc0 .LBB0_121
	v_mov_b32_e32 v2, v33
	v_mov_b32_e32 v3, v33
	v_mov_b32_e32 v0, v33
	v_mov_b32_e32 v1, v33
	v_mov_b64_e32 v[6:7], v[2:3]
	v_mov_b64_e32 v[4:5], v[0:1]
	s_branch .LBB0_122

; #define TJ_LOAD(tile_) do { const int n0_ = ((tile_) % ntn) * 64, k0_ = ((tile_) / ntn) * 64; const int sc_ = srccol<CM>(n0_ + cb); \
;     a = f32x4{0, 0, 0, 0}; b = f32x4{0, 0, 0, 0}; \
;     if (sc_ >= 0) { const float* s_ = src + (long)(k0_ + kk) * srcld + sc_; a = *(const f32x4*)s_; b = *(const f32x4*)(s_ + 4); } \
;     gg = g ? g[k0_ + kk] : 1.f; } while (0)
; template <int CM>
; DEVI void transpose_job(const float* __restrict__ src, int srcld, const float* __restrict__ g, bf16* __restrict__ dst,
;                         int K, int Ndst, unsigned short* lds, const int wave_u, const int vb, const int nvb) {
;   int tid = get_tid(wave_u);
;   const int ntn = Ndst / 64, ntiles = ntn * (K / 64);
;   const int kk = tid >> 3, cb = (tid & 7) * 8;
;   f32x4 a = {0, 0, 0, 0}, b = {0, 0, 0, 0}; float gg = 1.f;
;     ...
;   int tile = vb;
;   if (tile < ntiles) TJ_LOAD(tile);
;   for (; tile < ntiles; tile += nvb) {
;     const int n0 = (tile % ntn) * 64, k0 = (tile / ntn) * 64;
;     { u32x4 w = {cvtpk(a[0] * gg, a[1] * gg), cvtpk(a[2] * gg, a[3] * gg), cvtpk(b[0] * gg, b[1] * gg), cvtpk(b[2] * gg, b[3] * gg)};
;       *reinterpret_cast<u32x4*>(lds + kk * 72 + cb) = w; }
.LBB0_130:
	s_movk_i32 s4, 0x90
	v_mul_lo_u32 v13, v12, s4
	v_readlane_b32 s4, v252, 44
	v_lshl_add_u32 v11, v8, 1, 16
	v_lshl_add_u32 v14, v12, 1, 16
	v_mul_u32_u24_e32 v15, 0x90, v8
	v_readlane_b32 s39, v252, 55
	s_lshl_b32 s9, s4, 6
	s_lshl_b32 s8, s39, 6
	v_or_b32_e32 v10, s9, v8
	v_add_u32_e32 v11, v11, v13
	v_add_u32_e32 v13, v14, v15
	v_lshlrev_b32_e32 v32, 1, v8
	s_waitcnt vmcnt(0)
	s_branch .LBB0_133

; #define TJ_LOAD(tile_) do { const int n0_ = ((tile_) % ntn) * 64, k0_ = ((tile_) / ntn) * 64; const int sc_ = srccol<CM>(n0_ + cb); \
;     a = f32x4{0, 0, 0, 0}; b = f32x4{0, 0, 0, 0}; \
;     if (sc_ >= 0) { const float* s_ = src + (long)(k0_ + kk) * srcld + sc_; a = *(const f32x4*)s_; b = *(const f32x4*)(s_ + 4); } \
;     gg = g ? g[k0_ + kk] : 1.f; } while (0)
; template <int CM>
; DEVI void transpose_job(const float* __restrict__ src, int srcld, const float* __restrict__ g, bf16* __restrict__ dst,
;                         int K, int Ndst, unsigned short* lds, const int wave_u, const int vb, const int nvb) {
;     ...
;   for (; tile < ntiles; tile += nvb) {
;     const int n0 = (tile % ntn) * 64, k0 = (tile / ntn) * 64;
;     { u32x4 w = {cvtpk(a[0] * gg, a[1] * gg), cvtpk(a[2] * gg, a[3] * gg), cvtpk(b[0] * gg, b[1] * gg), cvtpk(b[2] * gg, b[3] * gg)};
;       *reinterpret_cast<u32x4*>(lds + kk * 72 + cb) = w; }
;     if (tile + nvb < ntiles) TJ_LOAD(tile + nvb);
;     __syncthreads();
;     { const int nn = tid >> 3, kb = (tid & 7) * 8; unsigned short e[8];
; #pragma unroll
;       for (int i = 0; i < 8; ++i) e[i] = lds[(kb + i) * 72 + nn];
;       u32x4 w = {(unsigned)e[0] | ((unsigned)e[1] << 16), (unsigned)e[2] | ((unsigned)e[3] << 16),
;                  (unsigned)e[4] | ((unsigned)e[5] << 16), (unsigned)e[6] | ((unsigned)e[7] << 16)};
;       *reinterpret_cast<u32x4*>(dst + (long)(n0 + nn) * K + k0 + kb) = w; }
;     __syncthreads();
.LBB0_133:
	v_readlane_b32 s4, v252, 44
	s_add_i32 s38, s39, s4
	s_waitcnt vmcnt(1)
	v_mul_f32_e32 v8, v4, v9
	v_mul_f32_e32 v14, v5, v9
	s_cmpk_gt_i32 s38, 0x3ff
	v_cvt_pk_bf16_f32 v14, v8, v14
	v_mul_f32_e32 v8, v6, v9
	v_mul_f32_e32 v15, v7, v9
	s_cselect_b64 s[6:7], -1, 0
	v_cvt_pk_bf16_f32 v15, v8, v15
	v_mul_f32_e32 v8, v9, v0
	v_mul_f32_e32 v16, v9, v1
	v_mul_f32_e32 v17, v9, v3
	s_and_b64 vcc, exec, s[6:7]
	v_cvt_pk_bf16_f32 v16, v8, v16
	v_mul_f32_e32 v8, v9, v2
	v_cvt_pk_bf16_f32 v17, v8, v17
	ds_write_b128 v11, v[14:17]
	s_cbranch_vccnz .LBB0_132
	s_ashr_i32 s4, s38, 31
	s_lshr_b32 s4, s4, 27
	s_add_i32 s4, s38, s4
	s_ashr_i32 s68, s4, 5
	s_andn2_b32 s4, s4, 31
	s_lshl_b32 s5, s68, 6
	s_sub_i32 s4, s38, s4
	v_add_u32_e32 v8, s5, v12
	s_cmp_lt_i32 s4, 0
	v_ashrrev_i32_e32 v9, 31, v8
	s_cbranch_scc1 .LBB0_136
	v_readlane_b32 s16, v251, 25
	v_lshlrev_b64 v[0:1], 13, v[8:9]
	v_readlane_b32 s30, v251, 39
	v_readlane_b32 s31, v251, 40
	v_add_u32_e32 v2, s8, v10
	s_lshl_b32 s4, s68, 11
	v_lshl_add_u64 v[0:1], s[30:31], 0, v[0:1]
	v_subrev_u32_e32 v2, s4, v2
	v_mov_b32_e32 v3, v33
	v_lshl_add_u64 v[4:5], v[2:3], 2, v[0:1]
	global_load_dwordx4 v[0:3], v[4:5], off offset:16
	s_nop 0
	global_load_dwordx4 v[4:7], v[4:5], off
	v_readlane_b32 s17, v251, 26
	v_readlane_b32 s18, v251, 27
	v_readlane_b32 s19, v251, 28
	v_readlane_b32 s20, v251, 29
	v_readlane_b32 s21, v251, 30
	v_readlane_b32 s22, v251, 31
	v_readlane_b32 s23, v251, 32
	v_readlane_b32 s24, v251, 33
	v_readlane_b32 s25, v251, 34
	v_readlane_b32 s26, v251, 35
	v_readlane_b32 s27, v251, 36
	v_readlane_b32 s28, v251, 37
	v_readlane_b32 s29, v251, 38
	s_branch .LBB0_137

; #define TJ_LOAD(tile_) do { const int n0_ = ((tile_) % ntn) * 64, k0_ = ((tile_) / ntn) * 64; const int sc_ = srccol<CM>(n0_ + cb); \
;     a = f32x4{0, 0, 0, 0}; b = f32x4{0, 0, 0, 0}; \
;     if (sc_ >= 0) { const float* s_ = src + (long)(k0_ + kk) * srcld + sc_; a = *(const f32x4*)s_; b = *(const f32x4*)(s_ + 4); } \
;     gg = g ? g[k0_ + kk] : 1.f; } while (0)
; template <int CM>
; DEVI void transpose_job(const float* __restrict__ src, int srcld, const float* __restrict__ g, bf16* __restrict__ dst,
;                         int K, int Ndst, unsigned short* lds, const int wave_u, const int vb, const int nvb) {
;     ...
;   int tile = vb;
;   if (tile < ntiles) TJ_LOAD(tile);
; DEVI void run_phase(const int ph, const Params& P, char* shmc, const int wave_u) {
;     ...
;         transpose_job<0>(P.w_ple, 2048, nullptr, w_ple_t, 256, 2048, tl, wave_u, vb, nvb);
.LBB0_139:
	v_readlane_b32 s0, v252, 56
	v_readlane_b32 s1, v252, 57
	s_andn2_b64 vcc, exec, s[0:1]
	s_waitcnt vmcnt(0)
	v_mbcnt_lo_u32_b32 v0, -1, 0
	v_mbcnt_hi_u32_b32 v0, -1, v0
	s_cbranch_vccnz .LBB0_146
	s_waitcnt lgkmcnt(0)
	v_or_b32_e32 v1, s5, v0
	v_lshlrev_b32_e32 v0, 3, v0
	v_and_b32_e32 v12, 56, v0
	v_readlane_b32 s0, v252, 51
	v_ashrrev_i32_e32 v8, 3, v1
	v_readlane_b32 s16, v251, 3
	v_or_b32_e32 v2, s0, v12
	v_readlane_b32 s0, v252, 54
	v_readlane_b32 s17, v251, 4
	v_lshlrev_b32_e32 v32, 2, v2
	v_add_u32_e32 v0, s0, v8
	v_ashrrev_i32_e32 v1, 31, v0
	v_lshlrev_b64 v[0:1], 13, v[0:1]
	v_lshl_add_u64 v[0:1], s[16:17], 0, v[0:1]
	v_lshl_add_u64 v[0:1], v[0:1], 0, v[32:33]
	global_load_dwordx4 v[4:7], v[0:1], off offset:16
	s_nop 0
	global_load_dwordx4 v[0:3], v[0:1], off
	s_movk_i32 s0, 0x90
	v_mul_lo_u32 v11, v8, s0
	v_readlane_b32 s0, v252, 44
	v_lshl_add_u32 v10, v12, 1, 16
	v_lshl_add_u32 v13, v8, 1, 16
	v_mul_u32_u24_e32 v14, 0x90, v12
	s_lshl_b32 s6, s0, 6
	v_or_b32_e32 v9, s6, v12
	v_add_u32_e32 v10, v10, v11
	v_add_u32_e32 v11, v13, v14
	v_lshlrev_b32_e32 v32, 1, v12
	v_readlane_b32 s7, v252, 50
	v_readlane_b32 s9, v252, 55
	v_readlane_b32 s18, v251, 5
	v_readlane_b32 s19, v251, 6
	v_readlane_b32 s20, v251, 7
	v_readlane_b32 s21, v251, 8
	v_readlane_b32 s22, v251, 9
	v_readlane_b32 s23, v251, 10
	s_waitcnt vmcnt(0)
	s_branch .LBB0_143

; #define TJ_LOAD(tile_) do { const int n0_ = ((tile_) % ntn) * 64, k0_ = ((tile_) / ntn) * 64; const int sc_ = srccol<CM>(n0_ + cb); \
;     a = f32x4{0, 0, 0, 0}; b = f32x4{0, 0, 0, 0}; \
;     if (sc_ >= 0) { const float* s_ = src + (long)(k0_ + kk) * srcld + sc_; a = *(const f32x4*)s_; b = *(const f32x4*)(s_ + 4); } \
;     gg = g ? g[k0_ + kk] : 1.f; } while (0)
; template <int CM>
; DEVI void transpose_job(const float* __restrict__ src, int srcld, const float* __restrict__ g, bf16* __restrict__ dst,
;                         int K, int Ndst, unsigned short* lds, const int wave_u, const int vb, const int nvb) {
;     ...
;   for (; tile < ntiles; tile += nvb) {
;     const int n0 = (tile % ntn) * 64, k0 = (tile / ntn) * 64;
;     { u32x4 w = {cvtpk(a[0] * gg, a[1] * gg), cvtpk(a[2] * gg, a[3] * gg), cvtpk(b[0] * gg, b[1] * gg), cvtpk(b[2] * gg, b[3] * gg)};
;       *reinterpret_cast<u32x4*>(lds + kk * 72 + cb) = w; }
;     if (tile + nvb < ntiles) TJ_LOAD(tile + nvb);
;     __syncthreads();
;     { const int nn = tid >> 3, kb = (tid & 7) * 8; unsigned short e[8];
; #pragma unroll
;       for (int i = 0; i < 8; ++i) e[i] = lds[(kb + i) * 72 + nn];
;       u32x4 w = {(unsigned)e[0] | ((unsigned)e[1] << 16), (unsigned)e[2] | ((unsigned)e[3] << 16),
;                  (unsigned)e[4] | ((unsigned)e[5] << 16), (unsigned)e[6] | ((unsigned)e[7] << 16)};
;       *reinterpret_cast<u32x4*>(dst + (long)(n0 + nn) * K + k0 + kb) = w; }
;     __syncthreads();
.LBB0_143:
	v_readlane_b32 s0, v252, 44
	s_add_i32 s8, s9, s0
	s_cmpk_gt_i32 s8, 0x7f
	s_cselect_b64 s[0:1], -1, 0
	s_and_b64 vcc, exec, s[0:1]
	s_waitcnt vmcnt(1)
	v_cvt_pk_bf16_f32 v12, v0, v1
	v_cvt_pk_bf16_f32 v13, v2, v3
	v_cvt_pk_bf16_f32 v14, v4, v5
	v_cvt_pk_bf16_f32 v15, v6, v7
	ds_write_b128 v10, v[12:15]
	s_cbranch_vccnz .LBB0_142
	s_ashr_i32 s4, s8, 31
	s_lshr_b32 s4, s4, 27
	s_add_i32 s38, s8, s4
	s_and_b32 s4, s38, 0xffffffe0
	s_sub_i32 s4, s8, s4
	s_cmp_lt_i32 s4, 0
	s_cbranch_scc0 .LBB0_141
	v_mov_b32_e32 v2, v33
	v_mov_b32_e32 v3, v33
	v_mov_b32_e32 v0, v33
	v_mov_b32_e32 v1, v33
	v_mov_b64_e32 v[6:7], v[2:3]
	v_mov_b64_e32 v[4:5], v[0:1]
	s_branch .LBB0_142

; #define TJ_LOAD(tile_) do { const int n0_ = ((tile_) % ntn) * 64, k0_ = ((tile_) / ntn) * 64; const int sc_ = srccol<CM>(n0_ + cb); \
;     a = f32x4{0, 0, 0, 0}; b = f32x4{0, 0, 0, 0}; \
;     if (sc_ >= 0) { const float* s_ = src + (long)(k0_ + kk) * srcld + sc_; a = *(const f32x4*)s_; b = *(const f32x4*)(s_ + 4); } \
;     gg = g ? g[k0_ + kk] : 1.f; } while (0)
; template <int CM>
; DEVI void transpose_job(const float* __restrict__ src, int srcld, const float* __restrict__ g, bf16* __restrict__ dst,
;                         int K, int Ndst, unsigned short* lds, const int wave_u, const int vb, const int nvb) {
;   int tid = get_tid(wave_u);
;   const int ntn = Ndst / 64, ntiles = ntn * (K / 64);
;   const int kk = tid >> 3, cb = (tid & 7) * 8;
;   f32x4 a = {0, 0, 0, 0}, b = {0, 0, 0, 0}; float gg = 1.f;
;     ...
;   int tile = vb;
;   if (tile < ntiles) TJ_LOAD(tile);
;   for (; tile < ntiles; tile += nvb) {
;     const int n0 = (tile % ntn) * 64, k0 = (tile / ntn) * 64;
;     { u32x4 w = {cvtpk(a[0] * gg, a[1] * gg), cvtpk(a[2] * gg, a[3] * gg), cvtpk(b[0] * gg, b[1] * gg), cvtpk(b[2] * gg, b[3] * gg)};
;       *reinterpret_cast<u32x4*>(lds + kk * 72 + cb) = w; }
.LBB0_191:
	s_movk_i32 s4, 0x90
	v_mul_lo_u32 v13, v12, s4
	v_readlane_b32 s4, v252, 58
	v_lshl_add_u32 v11, v8, 1, 16
	v_lshl_add_u32 v14, v12, 1, 16
	v_mul_u32_u24_e32 v15, 0x90, v8
	s_lshl_b32 s8, s4, 6
	v_or_b32_e32 v10, s8, v8
	v_add_u32_e32 v11, v11, v13
	v_add_u32_e32 v13, v14, v15
	v_lshlrev_b32_e32 v32, 1, v8
	v_readlane_b32 s9, v253, 1
	v_readlane_b32 s13, v253, 0
	s_waitcnt vmcnt(0)
	s_branch .LBB0_194

; #define TJ_LOAD(tile_) do { const int n0_ = ((tile_) % ntn) * 64, k0_ = ((tile_) / ntn) * 64; const int sc_ = srccol<CM>(n0_ + cb); \
;     a = f32x4{0, 0, 0, 0}; b = f32x4{0, 0, 0, 0}; \
;     if (sc_ >= 0) { const float* s_ = src + (long)(k0_ + kk) * srcld + sc_; a = *(const f32x4*)s_; b = *(const f32x4*)(s_ + 4); } \
;     gg = g ? g[k0_ + kk] : 1.f; } while (0)
; template <int CM>
; DEVI void transpose_job(const float* __restrict__ src, int srcld, const float* __restrict__ g, bf16* __restrict__ dst,
;                         int K, int Ndst, unsigned short* lds, const int wave_u, const int vb, const int nvb) {
;     ...
;   for (; tile < ntiles; tile += nvb) {
;     const int n0 = (tile % ntn) * 64, k0 = (tile / ntn) * 64;
;     { u32x4 w = {cvtpk(a[0] * gg, a[1] * gg), cvtpk(a[2] * gg, a[3] * gg), cvtpk(b[0] * gg, b[1] * gg), cvtpk(b[2] * gg, b[3] * gg)};
;       *reinterpret_cast<u32x4*>(lds + kk * 72 + cb) = w; }
;     if (tile + nvb < ntiles) TJ_LOAD(tile + nvb);
;     __syncthreads();
;     { const int nn = tid >> 3, kb = (tid & 7) * 8; unsigned short e[8];
; #pragma unroll
;       for (int i = 0; i < 8; ++i) e[i] = lds[(kb + i) * 72 + nn];
;       u32x4 w = {(unsigned)e[0] | ((unsigned)e[1] << 16), (unsigned)e[2] | ((unsigned)e[3] << 16),
;                  (unsigned)e[4] | ((unsigned)e[5] << 16), (unsigned)e[6] | ((unsigned)e[7] << 16)};
;       *reinterpret_cast<u32x4*>(dst + (long)(n0 + nn) * K + k0 + kb) = w; }
;     __syncthreads();
.LBB0_194:
	v_readlane_b32 s4, v252, 58
	s_add_i32 s12, s13, s4
	s_waitcnt vmcnt(1)
	v_mul_f32_e32 v8, v4, v9
	v_mul_f32_e32 v14, v5, v9
	s_cmpk_gt_i32 s12, 0xfff
	v_cvt_pk_bf16_f32 v14, v8, v14
	v_mul_f32_e32 v8, v6, v9
	v_mul_f32_e32 v15, v7, v9
	s_cselect_b64 s[6:7], -1, 0
	v_cvt_pk_bf16_f32 v15, v8, v15
	v_mul_f32_e32 v8, v9, v0
	v_mul_f32_e32 v16, v9, v1
	v_mul_f32_e32 v17, v9, v3
	s_and_b64 vcc, exec, s[6:7]
	v_cvt_pk_bf16_f32 v16, v8, v16
	v_mul_f32_e32 v8, v9, v2
	v_cvt_pk_bf16_f32 v17, v8, v17
	ds_write_b128 v11, v[14:17]
	s_cbranch_vccnz .LBB0_193
	s_ashr_i32 s4, s12, 31
	s_lshr_b32 s4, s4, 25
	s_add_i32 s4, s12, s4
	s_ashr_i32 s38, s4, 7
	s_and_b32 s4, s4, 0xffffff80
	s_lshl_b32 s5, s38, 6
	s_sub_i32 s4, s12, s4
	v_add_u32_e32 v8, s5, v12
	s_cmp_lt_i32 s4, 0
	v_ashrrev_i32_e32 v9, 31, v8
	s_cbranch_scc1 .LBB0_197
	v_readlane_b32 s16, v251, 25
	v_lshlrev_b64 v[0:1], 15, v[8:9]
	v_readlane_b32 s22, v251, 31
	v_readlane_b32 s23, v251, 32
	v_add_u32_e32 v2, s9, v10
	s_lshl_b32 s4, s38, 13
	v_lshl_add_u64 v[0:1], s[22:23], 0, v[0:1]
	v_subrev_u32_e32 v2, s4, v2
	v_mov_b32_e32 v3, v33
	v_lshl_add_u64 v[4:5], v[2:3], 2, v[0:1]
	global_load_dwordx4 v[0:3], v[4:5], off offset:16
	s_nop 0
	global_load_dwordx4 v[4:7], v[4:5], off
	v_readlane_b32 s17, v251, 26
	v_readlane_b32 s18, v251, 27
	v_readlane_b32 s19, v251, 28
	v_readlane_b32 s20, v251, 29
	v_readlane_b32 s21, v251, 30
	v_readlane_b32 s24, v251, 33
	v_readlane_b32 s25, v251, 34
	v_readlane_b32 s26, v251, 35
	v_readlane_b32 s27, v251, 36
	v_readlane_b32 s28, v251, 37
	v_readlane_b32 s29, v251, 38
	v_readlane_b32 s30, v251, 39
	v_readlane_b32 s31, v251, 40
	s_branch .LBB0_198

; #define TJ_LOAD(tile_) do { const int n0_ = ((tile_) % ntn) * 64, k0_ = ((tile_) / ntn) * 64; const int sc_ = srccol<CM>(n0_ + cb); \
;     a = f32x4{0, 0, 0, 0}; b = f32x4{0, 0, 0, 0}; \
;     if (sc_ >= 0) { const float* s_ = src + (long)(k0_ + kk) * srcld + sc_; a = *(const f32x4*)s_; b = *(const f32x4*)(s_ + 4); } \
;     gg = g ? g[k0_ + kk] : 1.f; } while (0)
; template <int CM>
; DEVI void transpose_job(const float* __restrict__ src, int srcld, const float* __restrict__ g, bf16* __restrict__ dst,
;                         int K, int Ndst, unsigned short* lds, const int wave_u, const int vb, const int nvb) {
;   int tid = get_tid(wave_u);
;   const int ntn = Ndst / 64, ntiles = ntn * (K / 64);
;   const int kk = tid >> 3, cb = (tid & 7) * 8;
;   f32x4 a = {0, 0, 0, 0}, b = {0, 0, 0, 0}; float gg = 1.f;
;     ...
;   int tile = vb;
;   if (tile < ntiles) TJ_LOAD(tile);
;   for (; tile < ntiles; tile += nvb) {
;     const int n0 = (tile % ntn) * 64, k0 = (tile / ntn) * 64;
;     { u32x4 w = {cvtpk(a[0] * gg, a[1] * gg), cvtpk(a[2] * gg, a[3] * gg), cvtpk(b[0] * gg, b[1] * gg), cvtpk(b[2] * gg, b[3] * gg)};
;       *reinterpret_cast<u32x4*>(lds + kk * 72 + cb) = w; }
.LBB0_813:
	s_movk_i32 s4, 0x90
	v_mul_lo_u32 v11, v9, s4
	v_readlane_b32 s4, v254, 28
	v_lshl_add_u32 v10, v8, 1, 16
	v_lshl_add_u32 v13, v9, 1, 16
	v_add_u32_e32 v16, s4, v9
	v_readlane_b32 s4, v254, 25
	v_mul_u32_u24_e32 v14, 0x90, v8
	s_mov_b32 s12, 0
	v_add_u32_e32 v17, s4, v8
	v_readlane_b32 s4, v254, 35
	v_add_u32_e32 v18, v10, v11
	v_add_u32_e32 v19, v13, v14
	v_lshlrev_b32_e32 v10, 1, v8
	s_mov_b32 s70, s4
	v_readlane_b32 s5, v254, 36
	s_waitcnt vmcnt(0)
	s_branch .LBB0_817

; #define TJ_LOAD(tile_) do { const int n0_ = ((tile_) % ntn) * 64, k0_ = ((tile_) / ntn) * 64; const int sc_ = srccol<CM>(n0_ + cb); \
;     a = f32x4{0, 0, 0, 0}; b = f32x4{0, 0, 0, 0}; \
;     if (sc_ >= 0) { const float* s_ = src + (long)(k0_ + kk) * srcld + sc_; a = *(const f32x4*)s_; b = *(const f32x4*)(s_ + 4); } \
;     gg = g ? g[k0_ + kk] : 1.f; } while (0)
; template <int CM> DEVI int srccol(int n) {
;   if (CM == 1) { return n < 4096 ? n : (n < 8192 ? n + 64 : (n < 8256 ? 4096 + jperm(n - 8192) : -1)); }
;   if (CM == 2) { int h = n / 192, c = n % 192; return c < 128 ? n : h * 192 + 128 + jperm(c - 128); }
; template <int CM>
; DEVI void transpose_job(const float* __restrict__ src, int srcld, const float* __restrict__ g, bf16* __restrict__ dst,
;                         int K, int Ndst, unsigned short* lds, const int wave_u, const int vb, const int nvb) {
;     ...
;   int tile = vb;
;   if (tile < ntiles) TJ_LOAD(tile);
;   for (; tile < ntiles; tile += nvb) {
;     const int n0 = (tile % ntn) * 64, k0 = (tile / ntn) * 64;
;     { u32x4 w = {cvtpk(a[0] * gg, a[1] * gg), cvtpk(a[2] * gg, a[3] * gg), cvtpk(b[0] * gg, b[1] * gg), cvtpk(b[2] * gg, b[3] * gg)};
;       *reinterpret_cast<u32x4*>(lds + kk * 72 + cb) = w; }
;     if (tile + nvb < ntiles) TJ_LOAD(tile + nvb);
;     __syncthreads();
;     { const int nn = tid >> 3, kb = (tid & 7) * 8; unsigned short e[8];
; #pragma unroll
;       for (int i = 0; i < 8; ++i) e[i] = lds[(kb + i) * 72 + nn];
;       u32x4 w = {(unsigned)e[0] | ((unsigned)e[1] << 16), (unsigned)e[2] | ((unsigned)e[3] << 16),
;                  (unsigned)e[4] | ((unsigned)e[5] << 16), (unsigned)e[6] | ((unsigned)e[7] << 16)};
;       *reinterpret_cast<u32x4*>(dst + (long)(n0 + nn) * K + k0 + kb) = w; }
;     __syncthreads();
.LBB0_817:
	v_readlane_b32 s4, v254, 26
	s_add_i32 s13, s70, s4
	s_waitcnt vmcnt(1)
	v_mul_f32_e32 v11, v4, v12
	v_mul_f32_e32 v13, v5, v12
	s_cmpk_gt_i32 s13, 0x107f
	v_cvt_pk_bf16_f32 v20, v11, v13
	v_mul_f32_e32 v11, v6, v12
	v_mul_f32_e32 v13, v7, v12
	s_cselect_b64 s[6:7], -1, 0
	v_cvt_pk_bf16_f32 v21, v11, v13
	v_mul_f32_e32 v11, v12, v0
	v_mul_f32_e32 v13, v12, v1
	s_and_b64 vcc, exec, s[6:7]
	v_cvt_pk_bf16_f32 v22, v11, v13
	v_mul_f32_e32 v11, v12, v2
	v_mul_f32_e32 v13, v12, v3
	v_cvt_pk_bf16_f32 v23, v11, v13
	ds_write_b128 v18, v[20:23]
	v_readlane_b32 s5, v254, 27
	s_cbranch_vccnz .LBB0_816
	s_mul_hi_i32 s8, s13, 0x3e0f83e1
	s_lshr_b32 s9, s8, 31
	s_ashr_i32 s71, s8, 5
	s_add_i32 s71, s71, s9
	s_mul_i32 s8, s71, 0x84
	s_sub_i32 s8, s13, s8
	s_mul_i32 s38, s71, 0xffffdf00
	v_lshl_or_b32 v12, s8, 6, v8
	s_add_i32 s8, s38, s12
	v_add_u32_e32 v0, s8, v17
	s_movk_i32 s4, 0xfff
	v_cmp_lt_i32_e32 vcc, s4, v0
	s_and_saveexec_b64 s[8:9], vcc
	s_cbranch_execz .LBB0_832
	v_readlane_b32 s4, v254, 30
	s_add_i32 s68, s4, s12
	s_add_i32 s68, s68, s38
	s_cmpk_gt_u32 s68, 0x1fff
	s_mov_b64 s[38:39], -1
	s_cbranch_scc0 .LBB0_829
	s_cmpk_gt_u32 s68, 0x203f
	v_mov_b32_e32 v1, -1
	s_cbranch_scc1 .LBB0_828
	v_add_u32_e32 v1, 0xffffe000, v0
	v_cmp_lt_u32_e32 vcc, 15, v1
	s_and_saveexec_b64 s[38:39], vcc
	s_cbranch_execz .LBB0_827
	v_cmp_lt_u32_e32 vcc, 31, v1
	s_and_saveexec_b64 s[68:69], vcc
	s_xor_b64 s[68:69], exec, s[68:69]
	v_add_u32_e32 v2, 0xffffdff0, v0
	v_cmp_gt_u32_e32 vcc, 48, v1
	s_nop 1
	v_cndmask_b32_e32 v1, v1, v2, vcc
	s_andn2_saveexec_b64 s[68:69], s[68:69]
	v_add_u32_e32 v1, 0xffffe010, v12
	s_or_b64 exec, exec, s[68:69]

; #define TJ_LOAD(tile_) do { const int n0_ = ((tile_) % ntn) * 64, k0_ = ((tile_) / ntn) * 64; const int sc_ = srccol<CM>(n0_ + cb); \
;     a = f32x4{0, 0, 0, 0}; b = f32x4{0, 0, 0, 0}; \
;     if (sc_ >= 0) { const float* s_ = src + (long)(k0_ + kk) * srcld + sc_; a = *(const f32x4*)s_; b = *(const f32x4*)(s_ + 4); } \
;     gg = g ? g[k0_ + kk] : 1.f; } while (0)
; template <int CM>
; DEVI void transpose_job(const float* __restrict__ src, int srcld, const float* __restrict__ g, bf16* __restrict__ dst,
;                         int K, int Ndst, unsigned short* lds, const int wave_u, const int vb, const int nvb) {
;   int tid = get_tid(wave_u);
;   const int ntn = Ndst / 64, ntiles = ntn * (K / 64);
;   const int kk = tid >> 3, cb = (tid & 7) * 8;
;   f32x4 a = {0, 0, 0, 0}, b = {0, 0, 0, 0}; float gg = 1.f;
;     ...
;   int tile = vb;
;   if (tile < ntiles) TJ_LOAD(tile);
;   for (; tile < ntiles; tile += nvb) {
;     const int n0 = (tile % ntn) * 64, k0 = (tile / ntn) * 64;
;     { u32x4 w = {cvtpk(a[0] * gg, a[1] * gg), cvtpk(a[2] * gg, a[3] * gg), cvtpk(b[0] * gg, b[1] * gg), cvtpk(b[2] * gg, b[3] * gg)};
;       *reinterpret_cast<u32x4*>(lds + kk * 72 + cb) = w; }
.LBB0_849:
	s_movk_i32 s4, 0x90
	v_mul_lo_u32 v11, v9, s4
	v_readlane_b32 s4, v254, 29
	v_lshl_add_u32 v10, v8, 1, 16
	v_lshl_add_u32 v13, v9, 1, 16
	v_mul_u32_u24_e32 v14, 0x90, v8
	v_add_u32_e32 v16, s4, v8
	v_readlane_b32 s4, v254, 35
	v_add_u32_e32 v17, v10, v11
	v_add_u32_e32 v18, v13, v14
	v_lshlrev_b32_e32 v10, 1, v8
	v_readlane_b32 s12, v254, 28
	s_mov_b32 s70, s4
	v_readlane_b32 s5, v254, 36
	s_waitcnt vmcnt(0)
	s_branch .LBB0_852

; #define TJ_LOAD(tile_) do { const int n0_ = ((tile_) % ntn) * 64, k0_ = ((tile_) / ntn) * 64; const int sc_ = srccol<CM>(n0_ + cb); \
;     a = f32x4{0, 0, 0, 0}; b = f32x4{0, 0, 0, 0}; \
;     if (sc_ >= 0) { const float* s_ = src + (long)(k0_ + kk) * srcld + sc_; a = *(const f32x4*)s_; b = *(const f32x4*)(s_ + 4); } \
;     gg = g ? g[k0_ + kk] : 1.f; } while (0)
; template <int CM> DEVI int srccol(int n) {
;     ...
;   if (CM == 2) { int h = n / 192, c = n % 192; return c < 128 ? n : h * 192 + 128 + jperm(c - 128); }
; template <int CM>
; DEVI void transpose_job(const float* __restrict__ src, int srcld, const float* __restrict__ g, bf16* __restrict__ dst,
;                         int K, int Ndst, unsigned short* lds, const int wave_u, const int vb, const int nvb) {
;     ...
;   int tile = vb;
;   if (tile < ntiles) TJ_LOAD(tile);
;   for (; tile < ntiles; tile += nvb) {
;     const int n0 = (tile % ntn) * 64, k0 = (tile / ntn) * 64;
;     { u32x4 w = {cvtpk(a[0] * gg, a[1] * gg), cvtpk(a[2] * gg, a[3] * gg), cvtpk(b[0] * gg, b[1] * gg), cvtpk(b[2] * gg, b[3] * gg)};
;       *reinterpret_cast<u32x4*>(lds + kk * 72 + cb) = w; }
;     if (tile + nvb < ntiles) TJ_LOAD(tile + nvb);
;     __syncthreads();
;     { const int nn = tid >> 3, kb = (tid & 7) * 8; unsigned short e[8];
; #pragma unroll
;       for (int i = 0; i < 8; ++i) e[i] = lds[(kb + i) * 72 + nn];
;       u32x4 w = {(unsigned)e[0] | ((unsigned)e[1] << 16), (unsigned)e[2] | ((unsigned)e[3] << 16),
;                  (unsigned)e[4] | ((unsigned)e[5] << 16), (unsigned)e[6] | ((unsigned)e[7] << 16)};
;       *reinterpret_cast<u32x4*>(dst + (long)(n0 + nn) * K + k0 + kb) = w; }
;     __syncthreads();
.LBB0_852:
	v_readlane_b32 s4, v254, 26
	s_add_i32 s13, s70, s4
	s_waitcnt vmcnt(1)
	v_mul_f32_e32 v11, v4, v12
	v_mul_f32_e32 v13, v5, v12
	s_cmpk_gt_i32 s13, 0xbf
	v_cvt_pk_bf16_f32 v20, v11, v13
	v_mul_f32_e32 v11, v6, v12
	v_mul_f32_e32 v13, v7, v12
	s_cselect_b64 s[6:7], -1, 0
	v_cvt_pk_bf16_f32 v21, v11, v13
	v_mul_f32_e32 v11, v12, v0
	v_mul_f32_e32 v13, v12, v1
	s_and_b64 vcc, exec, s[6:7]
	v_cvt_pk_bf16_f32 v22, v11, v13
	v_mul_f32_e32 v11, v12, v2
	v_mul_f32_e32 v13, v12, v3
	v_cvt_pk_bf16_f32 v23, v11, v13
	ds_write_b128 v17, v[20:23]
	v_readlane_b32 s5, v254, 27
	s_cbranch_vccnz .LBB0_851
	s_mul_hi_i32 s8, s13, 0x2aaaaaab
	s_lshr_b32 s9, s8, 31
	s_ashr_i32 s71, s8, 2
	s_add_i32 s71, s71, s9
	s_mul_i32 s8, s71, 0xfffffa00
	s_add_i32 s8, s8, s12
	v_add_u32_e32 v14, s8, v16
	v_mul_i32_i24_e32 v0, 0x2aab, v14
	v_lshrrev_b32_e32 v1, 31, v0
	v_lshrrev_b32_e32 v0, 21, v0
	v_add_u16_e32 v0, v0, v1
	v_mul_lo_u16_e32 v0, 0xc0, v0
	v_sub_u16_e32 v0, v14, v0
	s_movk_i32 s4, 0x7f
	v_cmp_lt_i16_e32 vcc, s4, v0
	s_and_saveexec_b64 s[8:9], vcc
	s_cbranch_execz .LBB0_861
	v_add_u32_e32 v1, 0xffffff80, v0
	v_cmp_lt_u32_e32 vcc, 15, v1
	s_and_saveexec_b64 s[38:39], vcc
	s_cbranch_execz .LBB0_860
	v_cmp_lt_u32_e32 vcc, 31, v1
	s_and_saveexec_b64 s[68:69], vcc
	s_xor_b64 s[68:69], exec, s[68:69]
	v_add_u32_e32 v2, 0xffffff70, v0
	v_cmp_gt_u32_e32 vcc, 48, v1
	s_nop 1
	v_cndmask_b32_e32 v1, v1, v2, vcc
	s_andn2_saveexec_b64 s[68:69], s[68:69]
	v_add_u32_e32 v1, 0xffffff90, v0
	s_or_b64 exec, exec, s[68:69]

; #define TJ_LOAD(tile_) do { const int n0_ = ((tile_) % ntn) * 64, k0_ = ((tile_) / ntn) * 64; const int sc_ = srccol<CM>(n0_ + cb); \
;     a = f32x4{0, 0, 0, 0}; b = f32x4{0, 0, 0, 0}; \
;     if (sc_ >= 0) { const float* s_ = src + (long)(k0_ + kk) * srcld + sc_; a = *(const f32x4*)s_; b = *(const f32x4*)(s_ + 4); } \
;     gg = g ? g[k0_ + kk] : 1.f; } while (0)
; template <int CM>
; DEVI void transpose_job(const float* __restrict__ src, int srcld, const float* __restrict__ g, bf16* __restrict__ dst,
;                         int K, int Ndst, unsigned short* lds, const int wave_u, const int vb, const int nvb) {
;   int tid = get_tid(wave_u);
;   const int ntn = Ndst / 64, ntiles = ntn * (K / 64);
;   const int kk = tid >> 3, cb = (tid & 7) * 8;
;   f32x4 a = {0, 0, 0, 0}, b = {0, 0, 0, 0}; float gg = 1.f;
;     ...
;   int tile = vb;
;   if (tile < ntiles) TJ_LOAD(tile);
;   for (; tile < ntiles; tile += nvb) {
;     const int n0 = (tile % ntn) * 64, k0 = (tile / ntn) * 64;
;     { u32x4 w = {cvtpk(a[0] * gg, a[1] * gg), cvtpk(a[2] * gg, a[3] * gg), cvtpk(b[0] * gg, b[1] * gg), cvtpk(b[2] * gg, b[3] * gg)};
;       *reinterpret_cast<u32x4*>(lds + kk * 72 + cb) = w; }
.LBB0_869:
	s_movk_i32 s4, 0x90
	v_mul_lo_u32 v12, v9, s4
	v_readlane_b32 s4, v254, 29
	v_lshl_add_u32 v11, v8, 1, 16
	v_lshl_add_u32 v13, v9, 1, 16
	v_mul_u32_u24_e32 v14, 0x90, v8
	v_add_u32_e32 v10, s4, v8
	v_readlane_b32 s4, v254, 35
	v_add_u32_e32 v11, v11, v12
	v_add_u32_e32 v12, v13, v14
	v_lshlrev_b32_e32 v32, 1, v8
	v_readlane_b32 s12, v254, 28
	s_mov_b32 s13, s4
	v_readlane_b32 s5, v254, 36
	s_waitcnt vmcnt(0)
	s_branch .LBB0_872

; #define TJ_LOAD(tile_) do { const int n0_ = ((tile_) % ntn) * 64, k0_ = ((tile_) / ntn) * 64; const int sc_ = srccol<CM>(n0_ + cb); \
;     a = f32x4{0, 0, 0, 0}; b = f32x4{0, 0, 0, 0}; \
;     if (sc_ >= 0) { const float* s_ = src + (long)(k0_ + kk) * srcld + sc_; a = *(const f32x4*)s_; b = *(const f32x4*)(s_ + 4); } \
;     gg = g ? g[k0_ + kk] : 1.f; } while (0)
; template <int CM>
; DEVI void transpose_job(const float* __restrict__ src, int srcld, const float* __restrict__ g, bf16* __restrict__ dst,
;                         int K, int Ndst, unsigned short* lds, const int wave_u, const int vb, const int nvb) {
;     ...
;   for (; tile < ntiles; tile += nvb) {
;     const int n0 = (tile % ntn) * 64, k0 = (tile / ntn) * 64;
;     { u32x4 w = {cvtpk(a[0] * gg, a[1] * gg), cvtpk(a[2] * gg, a[3] * gg), cvtpk(b[0] * gg, b[1] * gg), cvtpk(b[2] * gg, b[3] * gg)};
;       *reinterpret_cast<u32x4*>(lds + kk * 72 + cb) = w; }
;     if (tile + nvb < ntiles) TJ_LOAD(tile + nvb);
;     __syncthreads();
;     { const int nn = tid >> 3, kb = (tid & 7) * 8; unsigned short e[8];
; #pragma unroll
;       for (int i = 0; i < 8; ++i) e[i] = lds[(kb + i) * 72 + nn];
;       u32x4 w = {(unsigned)e[0] | ((unsigned)e[1] << 16), (unsigned)e[2] | ((unsigned)e[3] << 16),
;                  (unsigned)e[4] | ((unsigned)e[5] << 16), (unsigned)e[6] | ((unsigned)e[7] << 16)};
;       *reinterpret_cast<u32x4*>(dst + (long)(n0 + nn) * K + k0 + kb) = w; }
;     __syncthreads();
.LBB0_872:
	v_readlane_b32 s4, v254, 26
	s_add_i32 s38, s13, s4
	s_cmpk_gt_i32 s38, 0x7f
	s_cselect_b64 s[8:9], -1, 0
	s_and_b64 vcc, exec, s[8:9]
	s_waitcnt vmcnt(1)
	v_cvt_pk_bf16_f32 v14, v4, v5
	v_cvt_pk_bf16_f32 v15, v6, v7
	v_cvt_pk_bf16_f32 v16, v0, v1
	v_cvt_pk_bf16_f32 v17, v2, v3
	ds_write_b128 v11, v[14:17]
	v_readlane_b32 s5, v254, 27
	s_cbranch_vccnz .LBB0_871
	s_ashr_i32 s39, s38, 31
	s_lshr_b32 s39, s39, 28
	s_add_i32 s39, s38, s39
	s_and_b32 s68, s39, -16
	s_sub_i32 s68, s38, s68
	s_cmp_lt_i32 s68, 0
	s_cbranch_scc0 .LBB0_870
	v_mov_b32_e32 v7, 0
	v_mov_b32_e32 v6, 0
	v_mov_b32_e32 v5, 0
	v_mov_b32_e32 v4, 0
	v_mov_b32_e32 v3, 0
	v_mov_b32_e32 v2, 0
	v_mov_b32_e32 v1, 0
	v_mov_b32_e32 v0, 0
	s_branch .LBB0_871

; #define TJ_LOAD(tile_) do { const int n0_ = ((tile_) % ntn) * 64, k0_ = ((tile_) / ntn) * 64; const int sc_ = srccol<CM>(n0_ + cb); \
;     a = f32x4{0, 0, 0, 0}; b = f32x4{0, 0, 0, 0}; \
;     if (sc_ >= 0) { const float* s_ = src + (long)(k0_ + kk) * srcld + sc_; a = *(const f32x4*)s_; b = *(const f32x4*)(s_ + 4); } \
;     gg = g ? g[k0_ + kk] : 1.f; } while (0)
; template <int CM>
; DEVI void transpose_job(const float* __restrict__ src, int srcld, const float* __restrict__ g, bf16* __restrict__ dst,
;                         int K, int Ndst, unsigned short* lds, const int wave_u, const int vb, const int nvb) {
;   int tid = get_tid(wave_u);
;   const int ntn = Ndst / 64, ntiles = ntn * (K / 64);
;   const int kk = tid >> 3, cb = (tid & 7) * 8;
;   f32x4 a = {0, 0, 0, 0}, b = {0, 0, 0, 0}; float gg = 1.f;
;     ...
;   int tile = vb;
;   if (tile < ntiles) TJ_LOAD(tile);
;   for (; tile < ntiles; tile += nvb) {
;     const int n0 = (tile % ntn) * 64, k0 = (tile / ntn) * 64;
;     { u32x4 w = {cvtpk(a[0] * gg, a[1] * gg), cvtpk(a[2] * gg, a[3] * gg), cvtpk(b[0] * gg, b[1] * gg), cvtpk(b[2] * gg, b[3] * gg)};
;       *reinterpret_cast<u32x4*>(lds + kk * 72 + cb) = w; }
.LBB0_880:
	s_movk_i32 s4, 0x90
	v_mul_lo_u32 v12, v9, s4
	v_readlane_b32 s4, v254, 29
	s_add_u32 s0, s66, 0x2380000
	v_lshl_add_u32 v11, v8, 1, 16
	v_lshl_add_u32 v13, v9, 1, 16
	v_mul_u32_u24_e32 v14, 0x90, v8
	v_add_u32_e32 v10, s4, v8
	v_readlane_b32 s4, v254, 35
	s_addc_u32 s1, s67, 0
	v_add_u32_e32 v11, v11, v12
	v_add_u32_e32 v12, v13, v14
	v_lshlrev_b32_e32 v32, 1, v8
	v_readlane_b32 s8, v254, 28
	s_mov_b32 s9, s4
	v_readlane_b32 s5, v254, 36
	s_waitcnt vmcnt(0)
	s_branch .LBB0_883

; #define TJ_LOAD(tile_) do { const int n0_ = ((tile_) % ntn) * 64, k0_ = ((tile_) / ntn) * 64; const int sc_ = srccol<CM>(n0_ + cb); \
;     a = f32x4{0, 0, 0, 0}; b = f32x4{0, 0, 0, 0}; \
;     if (sc_ >= 0) { const float* s_ = src + (long)(k0_ + kk) * srcld + sc_; a = *(const f32x4*)s_; b = *(const f32x4*)(s_ + 4); } \
;     gg = g ? g[k0_ + kk] : 1.f; } while (0)
; template <int CM>
; DEVI void transpose_job(const float* __restrict__ src, int srcld, const float* __restrict__ g, bf16* __restrict__ dst,
;                         int K, int Ndst, unsigned short* lds, const int wave_u, const int vb, const int nvb) {
;     ...
;   for (; tile < ntiles; tile += nvb) {
;     const int n0 = (tile % ntn) * 64, k0 = (tile / ntn) * 64;
;     { u32x4 w = {cvtpk(a[0] * gg, a[1] * gg), cvtpk(a[2] * gg, a[3] * gg), cvtpk(b[0] * gg, b[1] * gg), cvtpk(b[2] * gg, b[3] * gg)};
;       *reinterpret_cast<u32x4*>(lds + kk * 72 + cb) = w; }
;     if (tile + nvb < ntiles) TJ_LOAD(tile + nvb);
;     __syncthreads();
;     { const int nn = tid >> 3, kb = (tid & 7) * 8; unsigned short e[8];
; #pragma unroll
;       for (int i = 0; i < 8; ++i) e[i] = lds[(kb + i) * 72 + nn];
;       u32x4 w = {(unsigned)e[0] | ((unsigned)e[1] << 16), (unsigned)e[2] | ((unsigned)e[3] << 16),
;                  (unsigned)e[4] | ((unsigned)e[5] << 16), (unsigned)e[6] | ((unsigned)e[7] << 16)};
;       *reinterpret_cast<u32x4*>(dst + (long)(n0 + nn) * K + k0 + kb) = w; }
;     __syncthreads();
.LBB0_883:
	v_readlane_b32 s4, v254, 26
	s_add_i32 s12, s9, s4
	s_cmpk_gt_i32 s12, 0x7f
	s_cselect_b64 s[6:7], -1, 0
	s_and_b64 vcc, exec, s[6:7]
	s_waitcnt vmcnt(1)
	v_cvt_pk_bf16_f32 v14, v4, v5
	v_cvt_pk_bf16_f32 v15, v6, v7
	v_cvt_pk_bf16_f32 v16, v0, v1
	v_cvt_pk_bf16_f32 v17, v2, v3
	ds_write_b128 v11, v[14:17]
	v_readlane_b32 s5, v254, 27
	s_cbranch_vccnz .LBB0_882
	s_ashr_i32 s13, s12, 31
	s_lshr_b32 s13, s13, 28
	s_add_i32 s13, s12, s13
	s_and_b32 s38, s13, -16
	s_sub_i32 s38, s12, s38
	s_cmp_lt_i32 s38, 0
	s_cbranch_scc0 .LBB0_881
	v_mov_b32_e32 v7, 0
	v_mov_b32_e32 v6, 0
	v_mov_b32_e32 v5, 0
	v_mov_b32_e32 v4, 0
	v_mov_b32_e32 v3, 0
	v_mov_b32_e32 v2, 0
	v_mov_b32_e32 v1, 0
	v_mov_b32_e32 v0, 0
	s_branch .LBB0_882

; #define TJ_LOAD(tile_) do { const int n0_ = ((tile_) % ntn) * 64, k0_ = ((tile_) / ntn) * 64; const int sc_ = srccol<CM>(n0_ + cb); \
;     a = f32x4{0, 0, 0, 0}; b = f32x4{0, 0, 0, 0}; \
;     if (sc_ >= 0) { const float* s_ = src + (long)(k0_ + kk) * srcld + sc_; a = *(const f32x4*)s_; b = *(const f32x4*)(s_ + 4); } \
;     gg = g ? g[k0_ + kk] : 1.f; } while (0)
; template <int CM>
; DEVI void transpose_job(const float* __restrict__ src, int srcld, const float* __restrict__ g, bf16* __restrict__ dst,
;                         int K, int Ndst, unsigned short* lds, const int wave_u, const int vb, const int nvb) {
;     ...
;   for (; tile < ntiles; tile += nvb) {
;     const int n0 = (tile % ntn) * 64, k0 = (tile / ntn) * 64;
;     { u32x4 w = {cvtpk(a[0] * gg, a[1] * gg), cvtpk(a[2] * gg, a[3] * gg), cvtpk(b[0] * gg, b[1] * gg), cvtpk(b[2] * gg, b[3] * gg)};
;       *reinterpret_cast<u32x4*>(lds + kk * 72 + cb) = w; }
;     if (tile + nvb < ntiles) TJ_LOAD(tile + nvb);
;     __syncthreads();
;     { const int nn = tid >> 3, kb = (tid & 7) * 8; unsigned short e[8];
; #pragma unroll
;       for (int i = 0; i < 8; ++i) e[i] = lds[(kb + i) * 72 + nn];
;       u32x4 w = {(unsigned)e[0] | ((unsigned)e[1] << 16), (unsigned)e[2] | ((unsigned)e[3] << 16),
;                  (unsigned)e[4] | ((unsigned)e[5] << 16), (unsigned)e[6] | ((unsigned)e[7] << 16)};
;       *reinterpret_cast<u32x4*>(dst + (long)(n0 + nn) * K + k0 + kb) = w; }
;     __syncthreads();
.LBB0_894:
	v_readlane_b32 s4, v254, 26
	s_add_i32 s38, s13, s4
	s_cmpk_gt_i32 s38, 0x3ff
	s_cselect_b64 s[8:9], -1, 0
	s_and_b64 vcc, exec, s[8:9]
	s_waitcnt vmcnt(1)
	v_cvt_pk_bf16_f32 v14, v4, v5
	v_cvt_pk_bf16_f32 v15, v6, v7
	v_cvt_pk_bf16_f32 v16, v0, v1
	v_cvt_pk_bf16_f32 v17, v2, v3
	ds_write_b128 v11, v[14:17]
	v_readlane_b32 s5, v254, 27
	s_cbranch_vccnz .LBB0_893
	s_ashr_i32 s39, s38, 31
	s_lshr_b32 s39, s39, 27
	s_add_i32 s39, s38, s39
	s_and_b32 s68, s39, 0xffffffe0
	s_sub_i32 s68, s38, s68
	s_cmp_lt_i32 s68, 0
	s_cbranch_scc0 .LBB0_892
	v_mov_b32_e32 v7, 0
	v_mov_b32_e32 v6, 0
	v_mov_b32_e32 v5, 0
	v_mov_b32_e32 v4, 0
	v_mov_b32_e32 v3, 0
	v_mov_b32_e32 v2, 0
	v_mov_b32_e32 v1, 0
	v_mov_b32_e32 v0, 0
	s_branch .LBB0_893

; #define TJ_LOAD(tile_) do { const int n0_ = ((tile_) % ntn) * 64, k0_ = ((tile_) / ntn) * 64; const int sc_ = srccol<CM>(n0_ + cb); \
;     a = f32x4{0, 0, 0, 0}; b = f32x4{0, 0, 0, 0}; \
;     if (sc_ >= 0) { const float* s_ = src + (long)(k0_ + kk) * srcld + sc_; a = *(const f32x4*)s_; b = *(const f32x4*)(s_ + 4); } \
;     gg = g ? g[k0_ + kk] : 1.f; } while (0)
; template <int CM>
; DEVI void transpose_job(const float* __restrict__ src, int srcld, const float* __restrict__ g, bf16* __restrict__ dst,
;                         int K, int Ndst, unsigned short* lds, const int wave_u, const int vb, const int nvb) {
;   int tid = get_tid(wave_u);
;   const int ntn = Ndst / 64, ntiles = ntn * (K / 64);
;   const int kk = tid >> 3, cb = (tid & 7) * 8;
;   f32x4 a = {0, 0, 0, 0}, b = {0, 0, 0, 0}; float gg = 1.f;
;     ...
;   int tile = vb;
;   if (tile < ntiles) TJ_LOAD(tile);
;   for (; tile < ntiles; tile += nvb) {
;     const int n0 = (tile % ntn) * 64, k0 = (tile / ntn) * 64;
;     { u32x4 w = {cvtpk(a[0] * gg, a[1] * gg), cvtpk(a[2] * gg, a[3] * gg), cvtpk(b[0] * gg, b[1] * gg), cvtpk(b[2] * gg, b[3] * gg)};
;       *reinterpret_cast<u32x4*>(lds + kk * 72 + cb) = w; }
.LBB0_902:
	s_movk_i32 s0, 0x90
	v_mul_lo_u32 v12, v9, s0
	v_readlane_b32 s0, v254, 29
	v_lshl_add_u32 v11, v8, 1, 16
	v_lshl_add_u32 v13, v9, 1, 16
	v_mul_u32_u24_e32 v14, 0x90, v8
	v_add_u32_e32 v10, s0, v8
	v_readlane_b32 s0, v254, 35
	v_add_u32_e32 v11, v11, v12
	v_add_u32_e32 v12, v13, v14
	v_lshlrev_b32_e32 v32, 1, v8
	v_readlane_b32 s6, v254, 28
	s_mov_b32 s7, s0
	v_readlane_b32 s1, v254, 36
	s_waitcnt vmcnt(0)
	s_branch .LBB0_905

; #define TJ_LOAD(tile_) do { const int n0_ = ((tile_) % ntn) * 64, k0_ = ((tile_) / ntn) * 64; const int sc_ = srccol<CM>(n0_ + cb); \
;     a = f32x4{0, 0, 0, 0}; b = f32x4{0, 0, 0, 0}; \
;     if (sc_ >= 0) { const float* s_ = src + (long)(k0_ + kk) * srcld + sc_; a = *(const f32x4*)s_; b = *(const f32x4*)(s_ + 4); } \
;     gg = g ? g[k0_ + kk] : 1.f; } while (0)
; template <int CM>
; DEVI void transpose_job(const float* __restrict__ src, int srcld, const float* __restrict__ g, bf16* __restrict__ dst,
;                         int K, int Ndst, unsigned short* lds, const int wave_u, const int vb, const int nvb) {
;     ...
;   for (; tile < ntiles; tile += nvb) {
;     const int n0 = (tile % ntn) * 64, k0 = (tile / ntn) * 64;
;     { u32x4 w = {cvtpk(a[0] * gg, a[1] * gg), cvtpk(a[2] * gg, a[3] * gg), cvtpk(b[0] * gg, b[1] * gg), cvtpk(b[2] * gg, b[3] * gg)};
;       *reinterpret_cast<u32x4*>(lds + kk * 72 + cb) = w; }
;     if (tile + nvb < ntiles) TJ_LOAD(tile + nvb);
;     __syncthreads();
;     { const int nn = tid >> 3, kb = (tid & 7) * 8; unsigned short e[8];
; #pragma unroll
;       for (int i = 0; i < 8; ++i) e[i] = lds[(kb + i) * 72 + nn];
;       u32x4 w = {(unsigned)e[0] | ((unsigned)e[1] << 16), (unsigned)e[2] | ((unsigned)e[3] << 16),
;                  (unsigned)e[4] | ((unsigned)e[5] << 16), (unsigned)e[6] | ((unsigned)e[7] << 16)};
;       *reinterpret_cast<u32x4*>(dst + (long)(n0 + nn) * K + k0 + kb) = w; }
;     __syncthreads();
.LBB0_905:
	v_readlane_b32 s0, v254, 26
	s_add_i32 s8, s7, s0
	v_readlane_b32 s1, v254, 27
	s_cmpk_gt_i32 s8, 0x3ff
	s_cselect_b64 s[0:1], -1, 0
	s_and_b64 vcc, exec, s[0:1]
	s_waitcnt vmcnt(1)
	v_cvt_pk_bf16_f32 v14, v4, v5
	v_cvt_pk_bf16_f32 v15, v6, v7
	v_cvt_pk_bf16_f32 v16, v0, v1
	v_cvt_pk_bf16_f32 v17, v2, v3
	ds_write_b128 v11, v[14:17]
	s_cbranch_vccnz .LBB0_904
	s_ashr_i32 s9, s8, 31
	s_lshr_b32 s9, s9, 27
	s_add_i32 s9, s8, s9
	s_and_b32 s12, s9, 0xffffffe0
	s_sub_i32 s12, s8, s12
	s_cmp_lt_i32 s12, 0
	s_cbranch_scc0 .LBB0_903
	v_mov_b32_e32 v7, 0
	v_mov_b32_e32 v6, 0
	v_mov_b32_e32 v5, 0
	v_mov_b32_e32 v4, 0
	v_mov_b32_e32 v3, 0
	v_mov_b32_e32 v2, 0
	v_mov_b32_e32 v1, 0
	v_mov_b32_e32 v0, 0
	s_branch .LBB0_904
